# weight-convert loops: next item's loads stay in flight during the LDS transpose (counted wait at loop bottom); flat stores/loads of the projection epilogue and mLSTM state replaced by global ones; on
# baseline (speedup 1.0000x reference)
.LBB0_46:
	s_or_b64 exec, exec, s[20:21]
	v_lshlrev_b32_e32 v1, 2, v130
	v_lshrrev_b32_e32 v133, 4, v130
	v_and_b32_e32 v132, 28, v1
	v_lshl_or_b32 v1, s24, 6, v133
	v_mad_i64_i32 v[2:3], s[18:19], v1, s30, 0
	v_add_u32_e32 v0, v0, v132
	s_mul_i32 s12, s90, 0x4100
	v_lshl_add_u64 v[2:3], v[2:3], 2, s[14:15]
	v_ashrrev_i32_e32 v1, 31, v0
	s_mov_b32 s13, 0
	s_add_i32 s20, s12, 0
	v_lshl_add_u64 v[60:61], v[0:1], 2, v[2:3]
	s_mul_i32 s12, s30, 0xf0
	v_lshl_add_u64 v[40:41], v[60:61], 0, s[12:13]
	s_lshl_b32 s12, s30, 4
	s_sub_u32 s14, 0, s12
	s_subb_u32 s15, 0, 0
	v_lshl_add_u64 v[0:1], v[40:41], 0, s[14:15]
	v_lshl_add_u64 v[8:9], v[0:1], 0, s[14:15]
	global_load_dwordx4 v[0:3], v[0:1], off nt
	s_nop 0
	global_load_dwordx4 v[4:7], v[8:9], off nt
	v_lshl_add_u64 v[8:9], v[8:9], 0, s[14:15]
	v_lshl_add_u64 v[16:17], v[8:9], 0, s[14:15]
	global_load_dwordx4 v[8:11], v[8:9], off nt
	s_nop 0
	global_load_dwordx4 v[12:15], v[16:17], off nt
	v_lshl_add_u64 v[16:17], v[16:17], 0, s[14:15]
	v_lshl_add_u64 v[24:25], v[16:17], 0, s[14:15]
	v_lshl_add_u64 v[28:29], v[24:25], 0, s[14:15]
	v_lshl_add_u64 v[32:33], v[28:29], 0, s[14:15]
	v_lshl_add_u64 v[36:37], v[32:33], 0, s[14:15]
	v_lshl_add_u64 v[42:43], v[36:37], 0, s[14:15]
	global_load_dwordx4 v[16:19], v[16:17], off nt
	s_nop 0
	global_load_dwordx4 v[20:23], v[24:25], off nt
	v_lshlrev_b32_e32 v64, 4, v130
	global_load_dwordx4 v[24:27], v[28:29], off nt
	v_and_b32_e32 v64, 0xf0, v64
	global_load_dwordx4 v[28:31], v[32:33], off nt
	v_add_u32_e32 v65, s20, v64
	global_load_dwordx4 v[32:35], v[36:37], off nt
	v_lshlrev_b32_e32 v64, 3, v130
	global_load_dwordx4 v[36:39], v[42:43], off nt
	v_lshl_add_u64 v[42:43], v[42:43], 0, s[14:15]
	v_lshl_add_u64 v[48:49], v[42:43], 0, s[14:15]
	global_load_dwordx4 v[44:47], v[42:43], off nt
	v_lshl_add_u64 v[42:43], v[48:49], 0, s[14:15]
	v_lshl_add_u64 v[56:57], v[42:43], 0, s[14:15]
	global_load_dwordx4 v[48:51], v[48:49], off nt
	s_nop 0
	global_load_dwordx4 v[52:55], v[42:43], off nt
	s_nop 0
	global_load_dwordx4 v[56:59], v[56:57], off nt
	s_nop 0
	global_load_dwordx4 v[40:43], v[40:41], off nt
	s_nop 0
	global_load_dwordx4 v[60:63], v[60:61], off nt
	v_lshrrev_b32_e32 v134, 3, v130
	v_and_b32_e32 v64, 56, v64
	v_mul_u32_u24_e32 v66, 0x104, v133
	v_mul_u32_u24_e32 v67, 0x104, v64
	v_lshlrev_b32_e32 v68, 2, v134
	v_mov_b32_e32 v129, 0
	v_add3_u32 v135, s20, v67, v68
	v_or_b32_e32 v136, 8, v134
	v_or_b32_e32 v137, 16, v134
	v_or_b32_e32 v138, 24, v134
	v_lshlrev_b32_e32 v128, 1, v64
	v_or_b32_e32 v139, 32, v134
	v_or_b32_e32 v140, 40, v134
	v_add_u32_e32 v141, v65, v66
	v_or_b32_e32 v142, 48, v134
	s_mov_b32 s31, s46
	v_or_b32_e32 v143, 56, v134
	s_waitcnt vmcnt(0)
	s_branch .LBB0_49

.LBB0_48:
	s_ashr_i32 s12, s30, 31
	s_lshr_b32 s12, s12, 26
	s_add_i32 s12, s30, s12
	ds_write2_b32 v141, v60, v61 offset1:1
	ds_write2_b32 v141, v62, v63 offset0:2 offset1:3
	v_add_u32_e32 v60, 0x410, v141
	s_ashr_i32 s12, s12, 6
	ds_write2_b32 v60, v56, v57 offset1:1
	v_add_u32_e32 v56, 0x418, v141
	s_abs_i32 s20, s12
	ds_write2_b32 v56, v58, v59 offset1:1
	v_add_u32_e32 v56, 0x820, v141
	v_cvt_f32_u32_e32 v144, s20
	ds_write2_b32 v56, v52, v53 offset1:1
	v_add_u32_e32 v52, 0x828, v141
	ds_write2_b32 v52, v54, v55 offset1:1
	v_add_u32_e32 v52, 0xc30, v141
	ds_write2_b32 v52, v48, v49 offset1:1
	v_add_u32_e32 v48, 0xc38, v141
	ds_write2_b32 v48, v50, v51 offset1:1
	v_add_u32_e32 v48, 0x1040, v141
	v_rcp_iflag_f32_e32 v144, v144
	ds_write2_b32 v48, v44, v45 offset1:1
	v_add_u32_e32 v44, 0x1048, v141
	ds_write2_b32 v44, v46, v47 offset1:1
	v_add_u32_e32 v44, 0x1450, v141
	ds_write2_b32 v44, v36, v37 offset1:1
	v_add_u32_e32 v36, 0x1458, v141
	ds_write2_b32 v36, v38, v39 offset1:1
	v_add_u32_e32 v36, 0x1860, v141
	v_mul_f32_e32 v61, 0x4f7ffffe, v144
	ds_write2_b32 v36, v32, v33 offset1:1
	v_add_u32_e32 v32, 0x1868, v141
	v_cvt_u32_f32_e32 v61, v61
	ds_write2_b32 v32, v34, v35 offset1:1
	v_add_u32_e32 v32, 0x1c70, v141
	ds_write2_b32 v32, v28, v29 offset1:1
	v_add_u32_e32 v28, 0x1c78, v141
	ds_write2_b32 v28, v30, v31 offset1:1
	v_add_u32_e32 v28, 0x2080, v141
	ds_write2_b32 v28, v24, v25 offset1:1
	v_add_u32_e32 v24, 0x2088, v141
	s_sub_i32 s23, 0, s20
	v_readfirstlane_b32 s24, v61
	ds_write2_b32 v24, v26, v27 offset1:1
	v_add_u32_e32 v24, 0x2490, v141
	s_mul_i32 s23, s23, s24
	ds_write2_b32 v24, v20, v21 offset1:1
	v_add_u32_e32 v20, 0x2498, v141
	s_mul_hi_u32 s23, s24, s23
	ds_write2_b32 v20, v22, v23 offset1:1
	v_add_u32_e32 v20, 0x28a0, v141
	s_abs_i32 s21, s17
	s_add_i32 s24, s24, s23
	ds_write2_b32 v20, v16, v17 offset1:1
	v_add_u32_e32 v16, 0x28a8, v141
	s_mul_hi_u32 s23, s21, s24
	ds_write2_b32 v16, v18, v19 offset1:1
	v_add_u32_e32 v16, 0x2cb0, v141
	s_mul_i32 s24, s23, s20
	ds_write2_b32 v16, v12, v13 offset1:1
	v_add_u32_e32 v12, 0x2cb8, v141
	s_xor_b32 s22, s17, s12
	s_sub_i32 s21, s21, s24
	ds_write2_b32 v12, v14, v15 offset1:1
	v_add_u32_e32 v12, 0x30c0, v141
	s_ashr_i32 s22, s22, 31
	s_add_i32 s25, s23, 1
	s_sub_i32 s24, s21, s20
	ds_write2_b32 v12, v8, v9 offset1:1
	v_add_u32_e32 v8, 0x30c8, v141
	s_cmp_ge_u32 s21, s20
	ds_write2_b32 v8, v10, v11 offset1:1
	v_add_u32_e32 v8, 0x34d0, v141
	s_cselect_b32 s23, s25, s23
	ds_write2_b32 v8, v4, v5 offset1:1
	v_add_u32_e32 v4, 0x34d8, v141
	s_cselect_b32 s21, s24, s21
	s_add_i32 s24, s23, 1
	ds_write2_b32 v4, v6, v7 offset1:1
	v_add_u32_e32 v4, 0x38e0, v141
	s_cmp_ge_u32 s21, s20
	ds_write2_b32 v4, v0, v1 offset1:1
	v_add_u32_e32 v0, 0x38e8, v141
	s_cselect_b32 s20, s24, s23
	ds_write2_b32 v0, v2, v3 offset1:1
	v_add_u32_e32 v0, 0x3cf0, v141
	s_xor_b32 s20, s20, s22
	ds_write2_b32 v0, v40, v41 offset1:1
	v_add_u32_e32 v0, 0x3cf8, v141
	s_sub_i32 s21, s20, s22
	ds_write2_b32 v0, v42, v43 offset1:1
	s_lshl_b32 s20, s21, 6
	s_mul_i32 s21, s21, s12
	s_waitcnt lgkmcnt(0)
	v_add_u32_e32 v24, 0x400, v135
	s_sub_i32 s12, s17, s21
	s_ashr_i32 s21, s20, 31
	ds_read2_b32 v[4:5], v135 offset0:65 offset1:73
	ds_read2_b32 v[6:7], v135 offset1:8
	ds_read2_b32 v[8:9], v135 offset0:130 offset1:138
	ds_read2_b32 v[10:11], v135 offset0:195 offset1:203
	ds_read2_b32 v[12:13], v24 offset0:4 offset1:12
	ds_read2_b32 v[14:15], v24 offset0:69 offset1:77
	ds_read2_b32 v[16:17], v24 offset0:134 offset1:142
	ds_read2_b32 v[18:19], v24 offset0:199 offset1:207
	s_lshl_b32 s12, s12, 6
	s_lshl_b64 s[20:21], s[20:21], 1
	s_add_u32 s10, s10, s20
	v_or_b32_e32 v22, s12, v134
	s_addc_u32 s11, s11, s21
	v_ashrrev_i32_e32 v23, 31, v22
	v_lshl_add_u64 v[20:21], s[10:11], 0, v[128:129]
	v_lshlrev_b64 v[22:23], 12, v[22:23]
	s_waitcnt lgkmcnt(0)
	v_cvt_pk_bf16_f32 v0, v6, v4
	v_cvt_pk_bf16_f32 v1, v8, v10
	v_cvt_pk_bf16_f32 v2, v12, v14
	v_cvt_pk_bf16_f32 v3, v16, v18
	v_lshl_add_u64 v[22:23], v[20:21], 0, v[22:23]
	v_or_b32_e32 v4, s12, v136
	global_store_dwordx4 v[22:23], v[0:3], off
	s_nop 1
	s_nop 1
	v_cvt_pk_bf16_f32 v0, v7, v5
	v_ashrrev_i32_e32 v5, 31, v4
	v_cvt_pk_bf16_f32 v1, v9, v11
	v_cvt_pk_bf16_f32 v2, v13, v15
	v_cvt_pk_bf16_f32 v3, v17, v19
	v_lshlrev_b64 v[4:5], 12, v[4:5]
	ds_read2_b32 v[6:7], v135 offset0:81 offset1:89
	ds_read2_b32 v[8:9], v135 offset0:16 offset1:24
	ds_read2_b32 v[10:11], v135 offset0:146 offset1:154
	ds_read2_b32 v[12:13], v135 offset0:211 offset1:219
	ds_read2_b32 v[14:15], v24 offset0:20 offset1:28
	ds_read2_b32 v[16:17], v24 offset0:85 offset1:93
	ds_read2_b32 v[18:19], v24 offset0:150 offset1:158
	ds_read2_b32 v[22:23], v24 offset0:215 offset1:223
	v_lshl_add_u64 v[4:5], v[20:21], 0, v[4:5]
	global_store_dwordx4 v[4:5], v[0:3], off
	v_or_b32_e32 v4, s12, v137
	v_ashrrev_i32_e32 v5, 31, v4
	v_lshlrev_b64 v[4:5], 12, v[4:5]
	s_waitcnt lgkmcnt(6)
	v_cvt_pk_bf16_f32 v0, v8, v6
	s_waitcnt lgkmcnt(4)
	v_cvt_pk_bf16_f32 v1, v10, v12
	s_waitcnt lgkmcnt(2)
	v_cvt_pk_bf16_f32 v2, v14, v16
	s_waitcnt lgkmcnt(0)
	v_cvt_pk_bf16_f32 v3, v18, v22
	v_lshl_add_u64 v[4:5], v[20:21], 0, v[4:5]
	global_store_dwordx4 v[4:5], v[0:3], off
	v_or_b32_e32 v4, s12, v138
	v_ashrrev_i32_e32 v5, 31, v4
	v_cvt_pk_bf16_f32 v0, v9, v7
	v_cvt_pk_bf16_f32 v1, v11, v13
	v_cvt_pk_bf16_f32 v2, v15, v17
	v_cvt_pk_bf16_f32 v3, v19, v23
	v_lshlrev_b64 v[4:5], 12, v[4:5]
	ds_read2_b32 v[6:7], v135 offset0:32 offset1:40
	ds_read2_b32 v[8:9], v135 offset0:97 offset1:105
	ds_read2_b32 v[10:11], v135 offset0:162 offset1:170
	ds_read2_b32 v[12:13], v135 offset0:227 offset1:235
	ds_read2_b32 v[14:15], v24 offset0:36 offset1:44
	ds_read2_b32 v[16:17], v24 offset0:101 offset1:109
	ds_read2_b32 v[18:19], v24 offset0:166 offset1:174
	ds_read2_b32 v[22:23], v24 offset0:231 offset1:239
	v_lshl_add_u64 v[4:5], v[20:21], 0, v[4:5]
	global_store_dwordx4 v[4:5], v[0:3], off
	v_or_b32_e32 v4, s12, v139
	v_ashrrev_i32_e32 v5, 31, v4
	v_lshlrev_b64 v[4:5], 12, v[4:5]
	s_waitcnt lgkmcnt(6)
	v_cvt_pk_bf16_f32 v0, v6, v8
	s_waitcnt lgkmcnt(4)
	v_cvt_pk_bf16_f32 v1, v10, v12
	s_waitcnt lgkmcnt(2)
	v_cvt_pk_bf16_f32 v2, v14, v16
	s_waitcnt lgkmcnt(0)
	v_cvt_pk_bf16_f32 v3, v18, v22
	v_lshl_add_u64 v[4:5], v[20:21], 0, v[4:5]
	global_store_dwordx4 v[4:5], v[0:3], off
	v_or_b32_e32 v4, s12, v140
	v_ashrrev_i32_e32 v5, 31, v4
	v_cvt_pk_bf16_f32 v0, v7, v9
	v_cvt_pk_bf16_f32 v1, v11, v13
	v_cvt_pk_bf16_f32 v2, v15, v17
	v_cvt_pk_bf16_f32 v3, v19, v23
	v_lshlrev_b64 v[4:5], 12, v[4:5]
	ds_read2_b32 v[6:7], v135 offset0:48 offset1:56
	ds_read2_b32 v[8:9], v135 offset0:113 offset1:121
	ds_read2_b32 v[10:11], v135 offset0:178 offset1:186
	ds_read2_b32 v[12:13], v135 offset0:243 offset1:251
	ds_read2_b32 v[14:15], v24 offset0:52 offset1:60
	ds_read2_b32 v[16:17], v24 offset0:117 offset1:125
	ds_read2_b32 v[18:19], v24 offset0:182 offset1:190
	ds_read2_b32 v[22:23], v24 offset0:247 offset1:255
	v_lshl_add_u64 v[4:5], v[20:21], 0, v[4:5]
	global_store_dwordx4 v[4:5], v[0:3], off
	v_or_b32_e32 v4, s12, v142
	v_ashrrev_i32_e32 v5, 31, v4
	v_lshlrev_b64 v[4:5], 12, v[4:5]
	s_waitcnt lgkmcnt(6)
	v_cvt_pk_bf16_f32 v0, v6, v8
	s_waitcnt lgkmcnt(4)
	v_cvt_pk_bf16_f32 v1, v10, v12
	s_waitcnt lgkmcnt(2)
	v_cvt_pk_bf16_f32 v2, v14, v16
	s_waitcnt lgkmcnt(0)
	v_cvt_pk_bf16_f32 v3, v18, v22
	v_lshl_add_u64 v[4:5], v[20:21], 0, v[4:5]
	global_store_dwordx4 v[4:5], v[0:3], off
	v_or_b32_e32 v4, s12, v143
	v_ashrrev_i32_e32 v5, 31, v4
	v_lshlrev_b64 v[4:5], 12, v[4:5]
	v_cvt_pk_bf16_f32 v0, v7, v9
	v_cvt_pk_bf16_f32 v1, v11, v13
	v_cvt_pk_bf16_f32 v2, v15, v17
	v_cvt_pk_bf16_f32 v3, v19, v23
	v_lshl_add_u64 v[4:5], v[20:21], 0, v[4:5]
	global_store_dwordx4 v[4:5], v[0:3], off
	s_waitcnt lgkmcnt(0)
	s_waitcnt vmcnt(8)
	v_mov_b64_e32 v[40:41], v[124:125]
	v_mov_b64_e32 v[28:29], v[92:93]
	v_mov_b64_e32 v[4:5], v[116:117]
	v_mov_b64_e32 v[8:9], v[112:113]
	v_mov_b64_e32 v[0:1], v[120:121]
	v_mov_b64_e32 v[12:13], v[108:109]
	v_mov_b64_e32 v[16:17], v[104:105]
	v_mov_b64_e32 v[20:21], v[100:101]
	v_mov_b64_e32 v[24:25], v[96:97]
	v_mov_b64_e32 v[32:33], v[88:89]
	v_mov_b64_e32 v[36:37], v[84:85]
	v_mov_b64_e32 v[44:45], v[80:81]
	v_mov_b64_e32 v[48:49], v[76:77]
	v_mov_b64_e32 v[52:53], v[72:73]
	v_mov_b64_e32 v[56:57], v[68:69]
	v_mov_b64_e32 v[60:61], v[64:65]
	s_andn2_b64 vcc, exec, s[18:19]
	v_mov_b64_e32 v[42:43], v[126:127]
	v_mov_b64_e32 v[2:3], v[122:123]
	v_mov_b64_e32 v[6:7], v[118:119]
	v_mov_b64_e32 v[10:11], v[114:115]
	v_mov_b64_e32 v[14:15], v[110:111]
	v_mov_b64_e32 v[18:19], v[106:107]
	v_mov_b64_e32 v[22:23], v[102:103]
	v_mov_b64_e32 v[26:27], v[98:99]
	v_mov_b64_e32 v[30:31], v[94:95]
	v_mov_b64_e32 v[34:35], v[90:91]
	v_mov_b64_e32 v[38:39], v[86:87]
	v_mov_b64_e32 v[46:47], v[82:83]
	v_mov_b64_e32 v[50:51], v[78:79]
	v_mov_b64_e32 v[54:55], v[74:75]
	v_mov_b64_e32 v[58:59], v[70:71]
	v_mov_b64_e32 v[62:63], v[66:67]
	s_mov_b32 s17, s33
	s_mov_b64 s[10:11], s[14:15]
	s_mov_b32 s30, s34
	s_cbranch_vccz .LBB0_75

.LBB0_173:
	v_cvt_pk_bf16_f32 v128, v128, v129
	v_cvt_pk_bf16_f32 v129, v130, v131
	v_cvt_pk_bf16_f32 v130, v132, v133
	v_cvt_pk_bf16_f32 v131, v134, v135
	v_lshl_add_u64 v[170:171], v[168:169], 0, v[144:145]
	global_store_dwordx4 v[170:171], v[128:131], off
	v_mov_b64_e32 v[134:135], v[98:99]
	s_and_b64 vcc, exec, s[4:5]
	v_mov_b64_e32 v[130:131], v[102:103]
	v_mov_b64_e32 v[128:129], v[100:101]
	v_mov_b64_e32 v[132:133], v[96:97]
	s_cbranch_vccnz .LBB0_175
	v_mul_f32_e32 v129, 0xbfb8aa3b, v96
	v_mul_f32_e32 v130, 0xbfb8aa3b, v101
	v_exp_f32_e32 v129, v129
	v_exp_f32_e32 v130, v130
	v_mul_f32_e32 v131, 0xbfb8aa3b, v102
	v_mul_f32_e32 v133, 0xbfb8aa3b, v98
	v_add_f32_e32 v129, 1.0, v129
	v_rcp_f32_e32 v132, v129
	v_add_f32_e32 v129, 1.0, v130
	v_mul_f32_e32 v130, 0xbfb8aa3b, v97
	v_exp_f32_e32 v130, v130
	v_exp_f32_e32 v131, v131
	v_exp_f32_e32 v133, v133
	v_mul_f32_e32 v128, 0xbfb8aa3b, v100
	v_add_f32_e32 v163, 1.0, v130
	v_add_f32_e32 v130, 1.0, v131
	v_add_f32_e32 v131, 1.0, v133
	v_mul_f32_e32 v133, 0xbfb8aa3b, v103
	v_mul_f32_e32 v134, 0xbfb8aa3b, v99
	v_exp_f32_e32 v128, v128
	v_exp_f32_e32 v133, v133
	v_exp_f32_e32 v135, v134
	v_rcp_f32_e32 v134, v131
	v_add_f32_e32 v128, 1.0, v128
	v_add_f32_e32 v131, 1.0, v133
	v_add_f32_e32 v133, 1.0, v135
	v_rcp_f32_e32 v128, v128
	v_rcp_f32_e32 v129, v129
	v_rcp_f32_e32 v130, v130
	v_rcp_f32_e32 v131, v131
	v_rcp_f32_e32 v135, v133
	v_rcp_f32_e32 v133, v163
	v_pk_mul_f32 v[128:129], v[100:101], v[128:129]
	v_pk_mul_f32 v[130:131], v[102:103], v[130:131]
	v_pk_mul_f32 v[134:135], v[98:99], v[134:135]
	v_pk_mul_f32 v[132:133], v[96:97], v[132:133]
.LBB0_175:
	s_lshl_b32 s0, s42, 4
	v_cvt_pk_bf16_f32 v128, v128, v129
	v_cvt_pk_bf16_f32 v129, v130, v131
	v_cvt_pk_bf16_f32 v130, v132, v133
	v_cvt_pk_bf16_f32 v131, v134, v135
	s_lshl_b32 s0, s0, 1
	global_store_dwordx4 v[170:171], v[128:131], off offset:256
	v_lshl_add_u64 v[168:169], v[168:169], 0, s[0:1]
	v_mov_b64_e32 v[134:135], v[90:91]
	v_mov_b64_e32 v[130:131], v[94:95]
	s_and_b64 vcc, exec, s[4:5]
	v_mov_b64_e32 v[128:129], v[92:93]
	v_mov_b64_e32 v[132:133], v[88:89]
	s_cbranch_vccnz .LBB0_177
	v_mul_f32_e32 v129, 0xbfb8aa3b, v88
	v_mul_f32_e32 v130, 0xbfb8aa3b, v93
	v_exp_f32_e32 v129, v129
	v_exp_f32_e32 v130, v130
	v_mul_f32_e32 v131, 0xbfb8aa3b, v94
	v_mul_f32_e32 v133, 0xbfb8aa3b, v90
	v_add_f32_e32 v129, 1.0, v129
	v_rcp_f32_e32 v132, v129
	v_add_f32_e32 v129, 1.0, v130
	v_mul_f32_e32 v130, 0xbfb8aa3b, v89
	v_exp_f32_e32 v130, v130
	v_exp_f32_e32 v131, v131
	v_exp_f32_e32 v133, v133
	v_mul_f32_e32 v128, 0xbfb8aa3b, v92
	v_add_f32_e32 v163, 1.0, v130
	v_add_f32_e32 v130, 1.0, v131
	v_add_f32_e32 v131, 1.0, v133
	v_mul_f32_e32 v133, 0xbfb8aa3b, v95
	v_mul_f32_e32 v134, 0xbfb8aa3b, v91
	v_exp_f32_e32 v128, v128
	v_exp_f32_e32 v133, v133
	v_exp_f32_e32 v135, v134
	v_rcp_f32_e32 v134, v131
	v_add_f32_e32 v128, 1.0, v128
	v_add_f32_e32 v131, 1.0, v133
	v_add_f32_e32 v133, 1.0, v135
	v_rcp_f32_e32 v128, v128
	v_rcp_f32_e32 v129, v129
	v_rcp_f32_e32 v130, v130
	v_rcp_f32_e32 v131, v131
	v_rcp_f32_e32 v135, v133
	v_rcp_f32_e32 v133, v163
	v_pk_mul_f32 v[128:129], v[92:93], v[128:129]
	v_pk_mul_f32 v[130:131], v[94:95], v[130:131]
	v_pk_mul_f32 v[134:135], v[90:91], v[134:135]
	v_pk_mul_f32 v[132:133], v[88:89], v[132:133]
.LBB0_177:
	v_cvt_pk_bf16_f32 v128, v128, v129
	v_cvt_pk_bf16_f32 v129, v130, v131
	v_cvt_pk_bf16_f32 v130, v132, v133
	v_cvt_pk_bf16_f32 v131, v134, v135
	v_lshl_add_u64 v[170:171], v[168:169], 0, v[144:145]
	global_store_dwordx4 v[170:171], v[128:131], off
	v_mov_b64_e32 v[134:135], v[82:83]
	s_and_b64 vcc, exec, s[4:5]
	v_mov_b64_e32 v[130:131], v[86:87]
	v_mov_b64_e32 v[128:129], v[84:85]
	v_mov_b64_e32 v[132:133], v[80:81]
	s_cbranch_vccnz .LBB0_179
	v_mul_f32_e32 v129, 0xbfb8aa3b, v80
	v_mul_f32_e32 v130, 0xbfb8aa3b, v85
	v_exp_f32_e32 v129, v129
	v_exp_f32_e32 v130, v130
	v_mul_f32_e32 v131, 0xbfb8aa3b, v86
	v_mul_f32_e32 v133, 0xbfb8aa3b, v82
	v_add_f32_e32 v129, 1.0, v129
	v_rcp_f32_e32 v132, v129
	v_add_f32_e32 v129, 1.0, v130
	v_mul_f32_e32 v130, 0xbfb8aa3b, v81
	v_exp_f32_e32 v130, v130
	v_exp_f32_e32 v131, v131
	v_exp_f32_e32 v133, v133
	v_mul_f32_e32 v128, 0xbfb8aa3b, v84
	v_add_f32_e32 v163, 1.0, v130
	v_add_f32_e32 v130, 1.0, v131
	v_add_f32_e32 v131, 1.0, v133
	v_mul_f32_e32 v133, 0xbfb8aa3b, v87
	v_mul_f32_e32 v134, 0xbfb8aa3b, v83
	v_exp_f32_e32 v128, v128
	v_exp_f32_e32 v133, v133
	v_exp_f32_e32 v135, v134
	v_rcp_f32_e32 v134, v131
	v_add_f32_e32 v128, 1.0, v128
	v_add_f32_e32 v131, 1.0, v133
	v_add_f32_e32 v133, 1.0, v135
	v_rcp_f32_e32 v128, v128
	v_rcp_f32_e32 v129, v129
	v_rcp_f32_e32 v130, v130
	v_rcp_f32_e32 v131, v131
	v_rcp_f32_e32 v135, v133
	v_rcp_f32_e32 v133, v163
	v_pk_mul_f32 v[128:129], v[84:85], v[128:129]
	v_pk_mul_f32 v[130:131], v[86:87], v[130:131]
	v_pk_mul_f32 v[134:135], v[82:83], v[134:135]
	v_pk_mul_f32 v[132:133], v[80:81], v[132:133]
.LBB0_179:
	v_cvt_pk_bf16_f32 v128, v128, v129
	v_cvt_pk_bf16_f32 v129, v130, v131
	v_cvt_pk_bf16_f32 v130, v132, v133
	v_cvt_pk_bf16_f32 v131, v134, v135
	global_store_dwordx4 v[170:171], v[128:131], off offset:256
	v_lshl_add_u64 v[168:169], v[168:169], 0, s[0:1]
	v_mov_b64_e32 v[134:135], v[74:75]
	v_mov_b64_e32 v[130:131], v[78:79]
	s_and_b64 vcc, exec, s[4:5]
	v_mov_b64_e32 v[128:129], v[76:77]
	v_mov_b64_e32 v[132:133], v[72:73]
	s_cbranch_vccnz .LBB0_181
	v_mul_f32_e32 v129, 0xbfb8aa3b, v72
	v_mul_f32_e32 v130, 0xbfb8aa3b, v77
	v_exp_f32_e32 v129, v129
	v_exp_f32_e32 v130, v130
	v_mul_f32_e32 v131, 0xbfb8aa3b, v78
	v_mul_f32_e32 v133, 0xbfb8aa3b, v74
	v_add_f32_e32 v129, 1.0, v129
	v_rcp_f32_e32 v132, v129
	v_add_f32_e32 v129, 1.0, v130
	v_mul_f32_e32 v130, 0xbfb8aa3b, v73
	v_exp_f32_e32 v130, v130
	v_exp_f32_e32 v131, v131
	v_exp_f32_e32 v133, v133
	v_mul_f32_e32 v128, 0xbfb8aa3b, v76
	v_add_f32_e32 v163, 1.0, v130
	v_add_f32_e32 v130, 1.0, v131
	v_add_f32_e32 v131, 1.0, v133
	v_mul_f32_e32 v133, 0xbfb8aa3b, v79
	v_mul_f32_e32 v134, 0xbfb8aa3b, v75
	v_exp_f32_e32 v128, v128
	v_exp_f32_e32 v133, v133
	v_exp_f32_e32 v135, v134
	v_rcp_f32_e32 v134, v131
	v_add_f32_e32 v128, 1.0, v128
	v_add_f32_e32 v131, 1.0, v133
	v_add_f32_e32 v133, 1.0, v135
	v_rcp_f32_e32 v128, v128
	v_rcp_f32_e32 v129, v129
	v_rcp_f32_e32 v130, v130
	v_rcp_f32_e32 v131, v131
	v_rcp_f32_e32 v135, v133
	v_rcp_f32_e32 v133, v163
	v_pk_mul_f32 v[128:129], v[76:77], v[128:129]
	v_pk_mul_f32 v[130:131], v[78:79], v[130:131]
	v_pk_mul_f32 v[134:135], v[74:75], v[134:135]
	v_pk_mul_f32 v[132:133], v[72:73], v[132:133]
.LBB0_181:
	v_cvt_pk_bf16_f32 v128, v128, v129
	v_cvt_pk_bf16_f32 v129, v130, v131
	v_cvt_pk_bf16_f32 v130, v132, v133
	v_cvt_pk_bf16_f32 v131, v134, v135
	v_lshl_add_u64 v[170:171], v[168:169], 0, v[144:145]
	global_store_dwordx4 v[170:171], v[128:131], off
	v_mov_b64_e32 v[134:135], v[66:67]
	s_and_b64 vcc, exec, s[4:5]
	v_mov_b64_e32 v[130:131], v[70:71]
	v_mov_b64_e32 v[128:129], v[68:69]
	v_mov_b64_e32 v[132:133], v[64:65]
	s_cbranch_vccnz .LBB0_183
	v_mul_f32_e32 v129, 0xbfb8aa3b, v64
	v_mul_f32_e32 v130, 0xbfb8aa3b, v69
	v_exp_f32_e32 v129, v129
	v_exp_f32_e32 v130, v130
	v_mul_f32_e32 v131, 0xbfb8aa3b, v70
	v_mul_f32_e32 v133, 0xbfb8aa3b, v66
	v_add_f32_e32 v129, 1.0, v129
	v_rcp_f32_e32 v132, v129
	v_add_f32_e32 v129, 1.0, v130
	v_mul_f32_e32 v130, 0xbfb8aa3b, v65
	v_exp_f32_e32 v130, v130
	v_exp_f32_e32 v131, v131
	v_exp_f32_e32 v133, v133
	v_mul_f32_e32 v128, 0xbfb8aa3b, v68
	v_add_f32_e32 v163, 1.0, v130
	v_add_f32_e32 v130, 1.0, v131
	v_add_f32_e32 v131, 1.0, v133
	v_mul_f32_e32 v133, 0xbfb8aa3b, v71
	v_mul_f32_e32 v134, 0xbfb8aa3b, v67
	v_exp_f32_e32 v128, v128
	v_exp_f32_e32 v133, v133
	v_exp_f32_e32 v135, v134
	v_rcp_f32_e32 v134, v131
	v_add_f32_e32 v128, 1.0, v128
	v_add_f32_e32 v131, 1.0, v133
	v_add_f32_e32 v133, 1.0, v135
	v_rcp_f32_e32 v128, v128
	v_rcp_f32_e32 v129, v129
	v_rcp_f32_e32 v130, v130
	v_rcp_f32_e32 v131, v131
	v_rcp_f32_e32 v135, v133
	v_rcp_f32_e32 v133, v163
	v_pk_mul_f32 v[128:129], v[68:69], v[128:129]
	v_pk_mul_f32 v[130:131], v[70:71], v[130:131]
	v_pk_mul_f32 v[134:135], v[66:67], v[134:135]
	v_pk_mul_f32 v[132:133], v[64:65], v[132:133]
.LBB0_183:
	s_mul_i32 s33, s42, 0x50
	v_cvt_pk_bf16_f32 v128, v128, v129
	v_cvt_pk_bf16_f32 v129, v130, v131
	v_cvt_pk_bf16_f32 v130, v132, v133
	v_cvt_pk_bf16_f32 v131, v134, v135
	s_lshl_b32 s42, s33, 1
	s_mov_b32 s43, s1
	global_store_dwordx4 v[170:171], v[128:131], off offset:256
	v_lshl_add_u64 v[168:169], v[168:169], 0, s[42:43]
	v_mov_b64_e32 v[134:135], v[58:59]
	v_mov_b64_e32 v[130:131], v[62:63]
	s_and_b64 vcc, exec, s[4:5]
	v_mov_b64_e32 v[128:129], v[60:61]
	v_mov_b64_e32 v[132:133], v[56:57]
	s_cbranch_vccnz .LBB0_185
	v_mul_f32_e32 v129, 0xbfb8aa3b, v56
	v_mul_f32_e32 v130, 0xbfb8aa3b, v61
	v_exp_f32_e32 v129, v129
	v_exp_f32_e32 v130, v130
	v_mul_f32_e32 v131, 0xbfb8aa3b, v62
	v_mul_f32_e32 v133, 0xbfb8aa3b, v58
	v_add_f32_e32 v129, 1.0, v129
	v_rcp_f32_e32 v132, v129
	v_add_f32_e32 v129, 1.0, v130
	v_mul_f32_e32 v130, 0xbfb8aa3b, v57
	v_exp_f32_e32 v130, v130
	v_exp_f32_e32 v131, v131
	v_exp_f32_e32 v133, v133
	v_mul_f32_e32 v128, 0xbfb8aa3b, v60
	v_add_f32_e32 v163, 1.0, v130
	v_add_f32_e32 v130, 1.0, v131
	v_add_f32_e32 v131, 1.0, v133
	v_mul_f32_e32 v133, 0xbfb8aa3b, v63
	v_mul_f32_e32 v134, 0xbfb8aa3b, v59
	v_exp_f32_e32 v128, v128
	v_exp_f32_e32 v133, v133
	v_exp_f32_e32 v135, v134
	v_rcp_f32_e32 v134, v131
	v_add_f32_e32 v128, 1.0, v128
	v_add_f32_e32 v131, 1.0, v133
	v_add_f32_e32 v133, 1.0, v135
	v_rcp_f32_e32 v128, v128
	v_rcp_f32_e32 v129, v129
	v_rcp_f32_e32 v130, v130
	v_rcp_f32_e32 v131, v131
	v_rcp_f32_e32 v135, v133
	v_rcp_f32_e32 v133, v163
	v_pk_mul_f32 v[128:129], v[60:61], v[128:129]
	v_pk_mul_f32 v[130:131], v[62:63], v[130:131]
	v_pk_mul_f32 v[134:135], v[58:59], v[134:135]
	v_pk_mul_f32 v[132:133], v[56:57], v[132:133]
.LBB0_185:
	v_cvt_pk_bf16_f32 v128, v128, v129
	v_cvt_pk_bf16_f32 v129, v130, v131
	v_cvt_pk_bf16_f32 v130, v132, v133
	v_cvt_pk_bf16_f32 v131, v134, v135
	v_lshl_add_u64 v[170:171], v[168:169], 0, v[144:145]
	global_store_dwordx4 v[170:171], v[128:131], off
	v_mov_b64_e32 v[134:135], v[50:51]
	s_and_b64 vcc, exec, s[4:5]
	v_mov_b64_e32 v[130:131], v[54:55]
	v_mov_b64_e32 v[128:129], v[52:53]
	v_mov_b64_e32 v[132:133], v[48:49]
	s_cbranch_vccnz .LBB0_187
	v_mul_f32_e32 v129, 0xbfb8aa3b, v48
	v_mul_f32_e32 v130, 0xbfb8aa3b, v53
	v_exp_f32_e32 v129, v129
	v_exp_f32_e32 v130, v130
	v_mul_f32_e32 v131, 0xbfb8aa3b, v54
	v_mul_f32_e32 v133, 0xbfb8aa3b, v50
	v_add_f32_e32 v129, 1.0, v129
	v_rcp_f32_e32 v132, v129
	v_add_f32_e32 v129, 1.0, v130
	v_mul_f32_e32 v130, 0xbfb8aa3b, v49
	v_exp_f32_e32 v130, v130
	v_exp_f32_e32 v131, v131
	v_exp_f32_e32 v133, v133
	v_mul_f32_e32 v128, 0xbfb8aa3b, v52
	v_add_f32_e32 v163, 1.0, v130
	v_add_f32_e32 v130, 1.0, v131
	v_add_f32_e32 v131, 1.0, v133
	v_mul_f32_e32 v133, 0xbfb8aa3b, v55
	v_mul_f32_e32 v134, 0xbfb8aa3b, v51
	v_exp_f32_e32 v128, v128
	v_exp_f32_e32 v133, v133
	v_exp_f32_e32 v135, v134
	v_rcp_f32_e32 v134, v131
	v_add_f32_e32 v128, 1.0, v128
	v_add_f32_e32 v131, 1.0, v133
	v_add_f32_e32 v133, 1.0, v135
	v_rcp_f32_e32 v128, v128
	v_rcp_f32_e32 v129, v129
	v_rcp_f32_e32 v130, v130
	v_rcp_f32_e32 v131, v131
	v_rcp_f32_e32 v135, v133
	v_rcp_f32_e32 v133, v163
	v_pk_mul_f32 v[128:129], v[52:53], v[128:129]
	v_pk_mul_f32 v[130:131], v[54:55], v[130:131]
	v_pk_mul_f32 v[134:135], v[50:51], v[134:135]
	v_pk_mul_f32 v[132:133], v[48:49], v[132:133]
.LBB0_187:
	v_cvt_pk_bf16_f32 v128, v128, v129
	v_cvt_pk_bf16_f32 v129, v130, v131
	v_cvt_pk_bf16_f32 v130, v132, v133
	v_cvt_pk_bf16_f32 v131, v134, v135
	global_store_dwordx4 v[170:171], v[128:131], off offset:256
	v_lshl_add_u64 v[168:169], v[168:169], 0, s[0:1]
	v_mov_b64_e32 v[134:135], v[42:43]
	v_mov_b64_e32 v[130:131], v[46:47]
	s_and_b64 vcc, exec, s[4:5]
	v_mov_b64_e32 v[128:129], v[44:45]
	v_mov_b64_e32 v[132:133], v[40:41]
	s_cbranch_vccnz .LBB0_189
	v_mul_f32_e32 v129, 0xbfb8aa3b, v40
	v_mul_f32_e32 v130, 0xbfb8aa3b, v45
	v_exp_f32_e32 v129, v129
	v_exp_f32_e32 v130, v130
	v_mul_f32_e32 v131, 0xbfb8aa3b, v46
	v_mul_f32_e32 v133, 0xbfb8aa3b, v42
	v_add_f32_e32 v129, 1.0, v129
	v_rcp_f32_e32 v132, v129
	v_add_f32_e32 v129, 1.0, v130
	v_mul_f32_e32 v130, 0xbfb8aa3b, v41
	v_exp_f32_e32 v130, v130
	v_exp_f32_e32 v131, v131
	v_exp_f32_e32 v133, v133
	v_mul_f32_e32 v128, 0xbfb8aa3b, v44
	v_add_f32_e32 v163, 1.0, v130
	v_add_f32_e32 v130, 1.0, v131
	v_add_f32_e32 v131, 1.0, v133
	v_mul_f32_e32 v133, 0xbfb8aa3b, v47
	v_mul_f32_e32 v134, 0xbfb8aa3b, v43
	v_exp_f32_e32 v128, v128
	v_exp_f32_e32 v133, v133
	v_exp_f32_e32 v135, v134
	v_rcp_f32_e32 v134, v131
	v_add_f32_e32 v128, 1.0, v128
	v_add_f32_e32 v131, 1.0, v133
	v_add_f32_e32 v133, 1.0, v135
	v_rcp_f32_e32 v128, v128
	v_rcp_f32_e32 v129, v129
	v_rcp_f32_e32 v130, v130
	v_rcp_f32_e32 v131, v131
	v_rcp_f32_e32 v135, v133
	v_rcp_f32_e32 v133, v163
	v_pk_mul_f32 v[128:129], v[44:45], v[128:129]
	v_pk_mul_f32 v[130:131], v[46:47], v[130:131]
	v_pk_mul_f32 v[134:135], v[42:43], v[134:135]
	v_pk_mul_f32 v[132:133], v[40:41], v[132:133]
.LBB0_189:
	v_cvt_pk_bf16_f32 v128, v128, v129
	v_cvt_pk_bf16_f32 v129, v130, v131
	v_cvt_pk_bf16_f32 v130, v132, v133
	v_cvt_pk_bf16_f32 v131, v134, v135
	v_lshl_add_u64 v[170:171], v[168:169], 0, v[144:145]
	global_store_dwordx4 v[170:171], v[128:131], off
	v_mov_b64_e32 v[134:135], v[34:35]
	s_and_b64 vcc, exec, s[4:5]
	v_mov_b64_e32 v[130:131], v[38:39]
	v_mov_b64_e32 v[128:129], v[36:37]
	v_mov_b64_e32 v[132:133], v[32:33]
	s_cbranch_vccnz .LBB0_191
	v_mul_f32_e32 v129, 0xbfb8aa3b, v32
	v_mul_f32_e32 v130, 0xbfb8aa3b, v37
	v_exp_f32_e32 v129, v129
	v_exp_f32_e32 v130, v130
	v_mul_f32_e32 v131, 0xbfb8aa3b, v38
	v_mul_f32_e32 v133, 0xbfb8aa3b, v34
	v_add_f32_e32 v129, 1.0, v129
	v_rcp_f32_e32 v132, v129
	v_add_f32_e32 v129, 1.0, v130
	v_mul_f32_e32 v130, 0xbfb8aa3b, v33
	v_exp_f32_e32 v130, v130
	v_exp_f32_e32 v131, v131
	v_exp_f32_e32 v133, v133
	v_mul_f32_e32 v128, 0xbfb8aa3b, v36
	v_add_f32_e32 v163, 1.0, v130
	v_add_f32_e32 v130, 1.0, v131
	v_add_f32_e32 v131, 1.0, v133
	v_mul_f32_e32 v133, 0xbfb8aa3b, v39
	v_mul_f32_e32 v134, 0xbfb8aa3b, v35
	v_exp_f32_e32 v128, v128
	v_exp_f32_e32 v133, v133
	v_exp_f32_e32 v135, v134
	v_rcp_f32_e32 v134, v131
	v_add_f32_e32 v128, 1.0, v128
	v_add_f32_e32 v131, 1.0, v133
	v_add_f32_e32 v133, 1.0, v135
	v_rcp_f32_e32 v128, v128
	v_rcp_f32_e32 v129, v129
	v_rcp_f32_e32 v130, v130
	v_rcp_f32_e32 v131, v131
	v_rcp_f32_e32 v135, v133
	v_rcp_f32_e32 v133, v163
	v_pk_mul_f32 v[128:129], v[36:37], v[128:129]
	v_pk_mul_f32 v[130:131], v[38:39], v[130:131]
	v_pk_mul_f32 v[134:135], v[34:35], v[134:135]
	v_pk_mul_f32 v[132:133], v[32:33], v[132:133]
.LBB0_191:
	v_cvt_pk_bf16_f32 v128, v128, v129
	v_cvt_pk_bf16_f32 v129, v130, v131
	v_cvt_pk_bf16_f32 v130, v132, v133
	v_cvt_pk_bf16_f32 v131, v134, v135
	global_store_dwordx4 v[170:171], v[128:131], off offset:256
	v_lshl_add_u64 v[168:169], v[168:169], 0, s[0:1]
	v_mov_b64_e32 v[134:135], v[26:27]
	v_mov_b64_e32 v[130:131], v[30:31]
	s_and_b64 vcc, exec, s[4:5]
	v_mov_b64_e32 v[128:129], v[28:29]
	v_mov_b64_e32 v[132:133], v[24:25]
	s_cbranch_vccnz .LBB0_193
	v_mul_f32_e32 v129, 0xbfb8aa3b, v24
	v_mul_f32_e32 v130, 0xbfb8aa3b, v29
	v_exp_f32_e32 v129, v129
	v_exp_f32_e32 v130, v130
	v_mul_f32_e32 v131, 0xbfb8aa3b, v30
	v_mul_f32_e32 v133, 0xbfb8aa3b, v26
	v_add_f32_e32 v129, 1.0, v129
	v_rcp_f32_e32 v132, v129
	v_add_f32_e32 v129, 1.0, v130
	v_mul_f32_e32 v130, 0xbfb8aa3b, v25
	v_exp_f32_e32 v130, v130
	v_exp_f32_e32 v131, v131
	v_exp_f32_e32 v133, v133
	v_mul_f32_e32 v128, 0xbfb8aa3b, v28
	v_add_f32_e32 v163, 1.0, v130
	v_add_f32_e32 v130, 1.0, v131
	v_add_f32_e32 v131, 1.0, v133
	v_mul_f32_e32 v133, 0xbfb8aa3b, v31
	v_mul_f32_e32 v134, 0xbfb8aa3b, v27
	v_exp_f32_e32 v128, v128
	v_exp_f32_e32 v133, v133
	v_exp_f32_e32 v135, v134
	v_rcp_f32_e32 v134, v131
	v_add_f32_e32 v128, 1.0, v128
	v_add_f32_e32 v131, 1.0, v133
	v_add_f32_e32 v133, 1.0, v135
	v_rcp_f32_e32 v128, v128
	v_rcp_f32_e32 v129, v129
	v_rcp_f32_e32 v130, v130
	v_rcp_f32_e32 v131, v131
	v_rcp_f32_e32 v135, v133
	v_rcp_f32_e32 v133, v163
	v_pk_mul_f32 v[128:129], v[28:29], v[128:129]
	v_pk_mul_f32 v[130:131], v[30:31], v[130:131]
	v_pk_mul_f32 v[134:135], v[26:27], v[134:135]
	v_pk_mul_f32 v[132:133], v[24:25], v[132:133]
.LBB0_193:
	v_cvt_pk_bf16_f32 v128, v128, v129
	v_cvt_pk_bf16_f32 v129, v130, v131
	v_cvt_pk_bf16_f32 v130, v132, v133
	v_cvt_pk_bf16_f32 v131, v134, v135
	v_lshl_add_u64 v[170:171], v[168:169], 0, v[144:145]
	global_store_dwordx4 v[170:171], v[128:131], off
	v_mov_b64_e32 v[134:135], v[18:19]
	s_and_b64 vcc, exec, s[4:5]
	v_mov_b64_e32 v[130:131], v[22:23]
	v_mov_b64_e32 v[128:129], v[20:21]
	v_mov_b64_e32 v[132:133], v[16:17]
	s_cbranch_vccnz .LBB0_195
	v_mul_f32_e32 v129, 0xbfb8aa3b, v16
	v_mul_f32_e32 v130, 0xbfb8aa3b, v21
	v_exp_f32_e32 v129, v129
	v_exp_f32_e32 v130, v130
	v_mul_f32_e32 v131, 0xbfb8aa3b, v22
	v_mul_f32_e32 v133, 0xbfb8aa3b, v18
	v_add_f32_e32 v129, 1.0, v129
	v_rcp_f32_e32 v132, v129
	v_add_f32_e32 v129, 1.0, v130
	v_mul_f32_e32 v130, 0xbfb8aa3b, v17
	v_exp_f32_e32 v130, v130
	v_exp_f32_e32 v131, v131
	v_exp_f32_e32 v133, v133
	v_mul_f32_e32 v128, 0xbfb8aa3b, v20
	v_add_f32_e32 v163, 1.0, v130
	v_add_f32_e32 v130, 1.0, v131
	v_add_f32_e32 v131, 1.0, v133
	v_mul_f32_e32 v133, 0xbfb8aa3b, v23
	v_mul_f32_e32 v134, 0xbfb8aa3b, v19
	v_exp_f32_e32 v128, v128
	v_exp_f32_e32 v133, v133
	v_exp_f32_e32 v135, v134
	v_rcp_f32_e32 v134, v131
	v_add_f32_e32 v128, 1.0, v128
	v_add_f32_e32 v131, 1.0, v133
	v_add_f32_e32 v133, 1.0, v135
	v_rcp_f32_e32 v128, v128
	v_rcp_f32_e32 v129, v129
	v_rcp_f32_e32 v130, v130
	v_rcp_f32_e32 v131, v131
	v_rcp_f32_e32 v135, v133
	v_rcp_f32_e32 v133, v163
	v_pk_mul_f32 v[128:129], v[20:21], v[128:129]
	v_pk_mul_f32 v[130:131], v[22:23], v[130:131]
	v_pk_mul_f32 v[134:135], v[18:19], v[134:135]
	v_pk_mul_f32 v[132:133], v[16:17], v[132:133]
.LBB0_195:
	v_cvt_pk_bf16_f32 v128, v128, v129
	v_cvt_pk_bf16_f32 v129, v130, v131
	v_cvt_pk_bf16_f32 v130, v132, v133
	v_cvt_pk_bf16_f32 v131, v134, v135
	global_store_dwordx4 v[170:171], v[128:131], off offset:256
	v_lshl_add_u64 v[168:169], v[168:169], 0, s[0:1]
	v_mov_b64_e32 v[134:135], v[10:11]
	v_mov_b64_e32 v[130:131], v[14:15]
	s_and_b64 vcc, exec, s[4:5]
	v_mov_b64_e32 v[128:129], v[12:13]
	v_mov_b64_e32 v[132:133], v[8:9]
	s_cbranch_vccnz .LBB0_197
	v_mul_f32_e32 v129, 0xbfb8aa3b, v8
	v_mul_f32_e32 v130, 0xbfb8aa3b, v13
	v_exp_f32_e32 v129, v129
	v_exp_f32_e32 v130, v130
	v_mul_f32_e32 v131, 0xbfb8aa3b, v14
	v_mul_f32_e32 v133, 0xbfb8aa3b, v10
	v_add_f32_e32 v129, 1.0, v129
	v_rcp_f32_e32 v132, v129
	v_add_f32_e32 v129, 1.0, v130
	v_mul_f32_e32 v130, 0xbfb8aa3b, v9
	v_exp_f32_e32 v130, v130
	v_exp_f32_e32 v131, v131
	v_exp_f32_e32 v133, v133
	v_mul_f32_e32 v128, 0xbfb8aa3b, v12
	v_add_f32_e32 v163, 1.0, v130
	v_add_f32_e32 v130, 1.0, v131
	v_add_f32_e32 v131, 1.0, v133
	v_mul_f32_e32 v133, 0xbfb8aa3b, v15
	v_mul_f32_e32 v134, 0xbfb8aa3b, v11
	v_exp_f32_e32 v128, v128
	v_exp_f32_e32 v133, v133
	v_exp_f32_e32 v135, v134
	v_rcp_f32_e32 v134, v131
	v_add_f32_e32 v128, 1.0, v128
	v_add_f32_e32 v131, 1.0, v133
	v_add_f32_e32 v133, 1.0, v135
	v_rcp_f32_e32 v128, v128
	v_rcp_f32_e32 v129, v129
	v_rcp_f32_e32 v130, v130
	v_rcp_f32_e32 v131, v131
	v_rcp_f32_e32 v135, v133
	v_rcp_f32_e32 v133, v163
	v_pk_mul_f32 v[128:129], v[12:13], v[128:129]
	v_pk_mul_f32 v[130:131], v[14:15], v[130:131]
	v_pk_mul_f32 v[134:135], v[10:11], v[134:135]
	v_pk_mul_f32 v[132:133], v[8:9], v[132:133]
.LBB0_197:
	v_cvt_pk_bf16_f32 v128, v128, v129
	v_cvt_pk_bf16_f32 v129, v130, v131
	v_cvt_pk_bf16_f32 v130, v132, v133
	v_cvt_pk_bf16_f32 v131, v134, v135
	v_lshl_add_u64 v[170:171], v[168:169], 0, v[144:145]
	global_store_dwordx4 v[170:171], v[128:131], off
	v_mov_b64_e32 v[134:135], v[2:3]
	s_and_b64 vcc, exec, s[4:5]
	v_mov_b64_e32 v[130:131], v[6:7]
	v_mov_b64_e32 v[128:129], v[4:5]
	v_mov_b64_e32 v[132:133], v[0:1]
	s_cbranch_vccnz .LBB0_199
	v_mul_f32_e32 v129, 0xbfb8aa3b, v0
	v_mul_f32_e32 v130, 0xbfb8aa3b, v5
	v_exp_f32_e32 v129, v129
	v_exp_f32_e32 v130, v130
	v_mul_f32_e32 v131, 0xbfb8aa3b, v6
	v_mul_f32_e32 v133, 0xbfb8aa3b, v2
	v_add_f32_e32 v129, 1.0, v129
	v_rcp_f32_e32 v132, v129
	v_add_f32_e32 v129, 1.0, v130
	v_mul_f32_e32 v130, 0xbfb8aa3b, v1
	v_exp_f32_e32 v130, v130
	v_exp_f32_e32 v131, v131
	v_exp_f32_e32 v133, v133
	v_mul_f32_e32 v128, 0xbfb8aa3b, v4
	v_add_f32_e32 v144, 1.0, v130
	v_add_f32_e32 v130, 1.0, v131
	v_add_f32_e32 v131, 1.0, v133
	v_mul_f32_e32 v133, 0xbfb8aa3b, v7
	v_mul_f32_e32 v134, 0xbfb8aa3b, v3
	v_exp_f32_e32 v128, v128
	v_exp_f32_e32 v133, v133
	v_exp_f32_e32 v135, v134
	v_rcp_f32_e32 v134, v131
	v_add_f32_e32 v128, 1.0, v128
	v_add_f32_e32 v131, 1.0, v133
	v_add_f32_e32 v133, 1.0, v135
	v_rcp_f32_e32 v128, v128
	v_rcp_f32_e32 v129, v129
	v_rcp_f32_e32 v130, v130
	v_rcp_f32_e32 v131, v131
	v_rcp_f32_e32 v135, v133
	v_rcp_f32_e32 v133, v144
	v_pk_mul_f32 v[128:129], v[4:5], v[128:129]
	v_pk_mul_f32 v[130:131], v[6:7], v[130:131]
	v_pk_mul_f32 v[134:135], v[2:3], v[134:135]
	v_pk_mul_f32 v[132:133], v[0:1], v[132:133]
.LBB0_199:
	v_cvt_pk_bf16_f32 v128, v128, v129
	v_cvt_pk_bf16_f32 v129, v130, v131
	v_cvt_pk_bf16_f32 v130, v132, v133
	v_cvt_pk_bf16_f32 v131, v134, v135
	s_mov_b32 s43, s1
	global_store_dwordx4 v[170:171], v[128:131], off offset:256
	s_mov_b64 s[4:5], 0
	s_nop 0
	v_lshl_add_u64 v[128:129], v[168:169], 0, s[42:43]

.LBB0_519:
	v_cvt_pk_bf16_f32 v128, v128, v129
	v_cvt_pk_bf16_f32 v129, v130, v131
	v_cvt_pk_bf16_f32 v130, v132, v133
	v_cvt_pk_bf16_f32 v131, v134, v135
	v_lshl_add_u64 v[132:133], v[172:173], 0, v[144:145]
	global_store_dwordx4 v[132:133], v[128:131], off
	v_mov_b64_e32 v[134:135], v[98:99]
	s_and_b64 vcc, exec, s[4:5]
	v_mov_b64_e32 v[130:131], v[102:103]
	v_mov_b64_e32 v[128:129], v[100:101]
	v_mov_b64_e32 v[132:133], v[96:97]
	s_cbranch_vccnz .LBB0_521
	v_mul_f32_e32 v129, 0xbfb8aa3b, v96
	v_mul_f32_e32 v130, 0xbfb8aa3b, v101
	v_exp_f32_e32 v129, v129
	v_exp_f32_e32 v130, v130
	v_mul_f32_e32 v131, 0xbfb8aa3b, v102
	v_mul_f32_e32 v133, 0xbfb8aa3b, v98
	v_add_f32_e32 v129, 1.0, v129
	v_rcp_f32_e32 v132, v129
	v_add_f32_e32 v129, 1.0, v130
	v_mul_f32_e32 v130, 0xbfb8aa3b, v97
	v_exp_f32_e32 v130, v130
	v_exp_f32_e32 v131, v131
	v_exp_f32_e32 v133, v133
	v_mul_f32_e32 v128, 0xbfb8aa3b, v100
	v_add_f32_e32 v169, 1.0, v130
	v_add_f32_e32 v130, 1.0, v131
	v_add_f32_e32 v131, 1.0, v133
	v_mul_f32_e32 v133, 0xbfb8aa3b, v103
	v_mul_f32_e32 v134, 0xbfb8aa3b, v99
	v_exp_f32_e32 v128, v128
	v_exp_f32_e32 v133, v133
	v_exp_f32_e32 v135, v134
	v_rcp_f32_e32 v134, v131
	v_add_f32_e32 v128, 1.0, v128
	v_add_f32_e32 v131, 1.0, v133
	v_add_f32_e32 v133, 1.0, v135
	v_rcp_f32_e32 v128, v128
	v_rcp_f32_e32 v129, v129
	v_rcp_f32_e32 v130, v130
	v_rcp_f32_e32 v131, v131
	v_rcp_f32_e32 v135, v133
	v_rcp_f32_e32 v133, v169
	v_pk_mul_f32 v[128:129], v[100:101], v[128:129]
	v_pk_mul_f32 v[130:131], v[102:103], v[130:131]
	v_pk_mul_f32 v[134:135], v[98:99], v[134:135]
	v_pk_mul_f32 v[132:133], v[96:97], v[132:133]
.LBB0_521:
	s_lshl_b32 s0, s34, 4
	v_mov_b32_e32 v171, v145
	v_cvt_pk_bf16_f32 v128, v128, v129
	v_cvt_pk_bf16_f32 v129, v130, v131
	v_cvt_pk_bf16_f32 v130, v132, v133
	v_cvt_pk_bf16_f32 v131, v134, v135
	v_lshl_add_u64 v[132:133], v[172:173], 0, v[170:171]
	s_lshl_b32 s0, s0, 1
	global_store_dwordx4 v[132:133], v[128:131], off
	v_lshl_add_u64 v[172:173], v[172:173], 0, s[0:1]
	v_mov_b64_e32 v[134:135], v[90:91]
	v_mov_b64_e32 v[130:131], v[94:95]
	s_and_b64 vcc, exec, s[4:5]
	v_mov_b64_e32 v[128:129], v[92:93]
	v_mov_b64_e32 v[132:133], v[88:89]
	s_cbranch_vccnz .LBB0_523
	v_mul_f32_e32 v129, 0xbfb8aa3b, v88
	v_mul_f32_e32 v130, 0xbfb8aa3b, v93
	v_exp_f32_e32 v129, v129
	v_exp_f32_e32 v130, v130
	v_mul_f32_e32 v131, 0xbfb8aa3b, v94
	v_mul_f32_e32 v133, 0xbfb8aa3b, v90
	v_add_f32_e32 v129, 1.0, v129
	v_rcp_f32_e32 v132, v129
	v_add_f32_e32 v129, 1.0, v130
	v_mul_f32_e32 v130, 0xbfb8aa3b, v89
	v_exp_f32_e32 v130, v130
	v_exp_f32_e32 v131, v131
	v_exp_f32_e32 v133, v133
	v_mul_f32_e32 v128, 0xbfb8aa3b, v92
	v_add_f32_e32 v169, 1.0, v130
	v_add_f32_e32 v130, 1.0, v131
	v_add_f32_e32 v131, 1.0, v133
	v_mul_f32_e32 v133, 0xbfb8aa3b, v95
	v_mul_f32_e32 v134, 0xbfb8aa3b, v91
	v_exp_f32_e32 v128, v128
	v_exp_f32_e32 v133, v133
	v_exp_f32_e32 v135, v134
	v_rcp_f32_e32 v134, v131
	v_add_f32_e32 v128, 1.0, v128
	v_add_f32_e32 v131, 1.0, v133
	v_add_f32_e32 v133, 1.0, v135
	v_rcp_f32_e32 v128, v128
	v_rcp_f32_e32 v129, v129
	v_rcp_f32_e32 v130, v130
	v_rcp_f32_e32 v131, v131
	v_rcp_f32_e32 v135, v133
	v_rcp_f32_e32 v133, v169
	v_pk_mul_f32 v[128:129], v[92:93], v[128:129]
	v_pk_mul_f32 v[130:131], v[94:95], v[130:131]
	v_pk_mul_f32 v[134:135], v[90:91], v[134:135]
	v_pk_mul_f32 v[132:133], v[88:89], v[132:133]
.LBB0_523:
	v_cvt_pk_bf16_f32 v128, v128, v129
	v_cvt_pk_bf16_f32 v129, v130, v131
	v_cvt_pk_bf16_f32 v130, v132, v133
	v_cvt_pk_bf16_f32 v131, v134, v135
	v_lshl_add_u64 v[132:133], v[172:173], 0, v[144:145]
	global_store_dwordx4 v[132:133], v[128:131], off
	v_mov_b64_e32 v[134:135], v[82:83]
	s_and_b64 vcc, exec, s[4:5]
	v_mov_b64_e32 v[130:131], v[86:87]
	v_mov_b64_e32 v[128:129], v[84:85]
	v_mov_b64_e32 v[132:133], v[80:81]
	s_cbranch_vccnz .LBB0_525
	v_mul_f32_e32 v129, 0xbfb8aa3b, v80
	v_mul_f32_e32 v130, 0xbfb8aa3b, v85
	v_exp_f32_e32 v129, v129
	v_exp_f32_e32 v130, v130
	v_mul_f32_e32 v131, 0xbfb8aa3b, v86
	v_mul_f32_e32 v133, 0xbfb8aa3b, v82
	v_add_f32_e32 v129, 1.0, v129
	v_rcp_f32_e32 v132, v129
	v_add_f32_e32 v129, 1.0, v130
	v_mul_f32_e32 v130, 0xbfb8aa3b, v81
	v_exp_f32_e32 v130, v130
	v_exp_f32_e32 v131, v131
	v_exp_f32_e32 v133, v133
	v_mul_f32_e32 v128, 0xbfb8aa3b, v84
	v_add_f32_e32 v169, 1.0, v130
	v_add_f32_e32 v130, 1.0, v131
	v_add_f32_e32 v131, 1.0, v133
	v_mul_f32_e32 v133, 0xbfb8aa3b, v87
	v_mul_f32_e32 v134, 0xbfb8aa3b, v83
	v_exp_f32_e32 v128, v128
	v_exp_f32_e32 v133, v133
	v_exp_f32_e32 v135, v134
	v_rcp_f32_e32 v134, v131
	v_add_f32_e32 v128, 1.0, v128
	v_add_f32_e32 v131, 1.0, v133
	v_add_f32_e32 v133, 1.0, v135
	v_rcp_f32_e32 v128, v128
	v_rcp_f32_e32 v129, v129
	v_rcp_f32_e32 v130, v130
	v_rcp_f32_e32 v131, v131
	v_rcp_f32_e32 v135, v133
	v_rcp_f32_e32 v133, v169
	v_pk_mul_f32 v[128:129], v[84:85], v[128:129]
	v_pk_mul_f32 v[130:131], v[86:87], v[130:131]
	v_pk_mul_f32 v[134:135], v[82:83], v[134:135]
	v_pk_mul_f32 v[132:133], v[80:81], v[132:133]
.LBB0_525:
	v_mov_b32_e32 v171, v145
	v_cvt_pk_bf16_f32 v128, v128, v129
	v_cvt_pk_bf16_f32 v129, v130, v131
	v_cvt_pk_bf16_f32 v130, v132, v133
	v_cvt_pk_bf16_f32 v131, v134, v135
	v_lshl_add_u64 v[132:133], v[172:173], 0, v[170:171]
	global_store_dwordx4 v[132:133], v[128:131], off
	v_lshl_add_u64 v[172:173], v[172:173], 0, s[0:1]
	v_mov_b64_e32 v[134:135], v[74:75]
	v_mov_b64_e32 v[130:131], v[78:79]
	s_and_b64 vcc, exec, s[4:5]
	v_mov_b64_e32 v[128:129], v[76:77]
	v_mov_b64_e32 v[132:133], v[72:73]
	s_cbranch_vccnz .LBB0_527
	v_mul_f32_e32 v129, 0xbfb8aa3b, v72
	v_mul_f32_e32 v130, 0xbfb8aa3b, v77
	v_exp_f32_e32 v129, v129
	v_exp_f32_e32 v130, v130
	v_mul_f32_e32 v131, 0xbfb8aa3b, v78
	v_mul_f32_e32 v133, 0xbfb8aa3b, v74
	v_add_f32_e32 v129, 1.0, v129
	v_rcp_f32_e32 v132, v129
	v_add_f32_e32 v129, 1.0, v130
	v_mul_f32_e32 v130, 0xbfb8aa3b, v73
	v_exp_f32_e32 v130, v130
	v_exp_f32_e32 v131, v131
	v_exp_f32_e32 v133, v133
	v_mul_f32_e32 v128, 0xbfb8aa3b, v76
	v_add_f32_e32 v169, 1.0, v130
	v_add_f32_e32 v130, 1.0, v131
	v_add_f32_e32 v131, 1.0, v133
	v_mul_f32_e32 v133, 0xbfb8aa3b, v79
	v_mul_f32_e32 v134, 0xbfb8aa3b, v75
	v_exp_f32_e32 v128, v128
	v_exp_f32_e32 v133, v133
	v_exp_f32_e32 v135, v134
	v_rcp_f32_e32 v134, v131
	v_add_f32_e32 v128, 1.0, v128
	v_add_f32_e32 v131, 1.0, v133
	v_add_f32_e32 v133, 1.0, v135
	v_rcp_f32_e32 v128, v128
	v_rcp_f32_e32 v129, v129
	v_rcp_f32_e32 v130, v130
	v_rcp_f32_e32 v131, v131
	v_rcp_f32_e32 v135, v133
	v_rcp_f32_e32 v133, v169
	v_pk_mul_f32 v[128:129], v[76:77], v[128:129]
	v_pk_mul_f32 v[130:131], v[78:79], v[130:131]
	v_pk_mul_f32 v[134:135], v[74:75], v[134:135]
	v_pk_mul_f32 v[132:133], v[72:73], v[132:133]
.LBB0_527:
	v_cvt_pk_bf16_f32 v128, v128, v129
	v_cvt_pk_bf16_f32 v129, v130, v131
	v_cvt_pk_bf16_f32 v130, v132, v133
	v_cvt_pk_bf16_f32 v131, v134, v135
	v_lshl_add_u64 v[132:133], v[172:173], 0, v[144:145]
	global_store_dwordx4 v[132:133], v[128:131], off
	v_mov_b64_e32 v[134:135], v[66:67]
	s_and_b64 vcc, exec, s[4:5]
	v_mov_b64_e32 v[130:131], v[70:71]
	v_mov_b64_e32 v[128:129], v[68:69]
	v_mov_b64_e32 v[132:133], v[64:65]
	s_cbranch_vccnz .LBB0_529
	v_mul_f32_e32 v129, 0xbfb8aa3b, v64
	v_mul_f32_e32 v130, 0xbfb8aa3b, v69
	v_exp_f32_e32 v129, v129
	v_exp_f32_e32 v130, v130
	v_mul_f32_e32 v131, 0xbfb8aa3b, v70
	v_mul_f32_e32 v133, 0xbfb8aa3b, v66
	v_add_f32_e32 v129, 1.0, v129
	v_rcp_f32_e32 v132, v129
	v_add_f32_e32 v129, 1.0, v130
	v_mul_f32_e32 v130, 0xbfb8aa3b, v65
	v_exp_f32_e32 v130, v130
	v_exp_f32_e32 v131, v131
	v_exp_f32_e32 v133, v133
	v_mul_f32_e32 v128, 0xbfb8aa3b, v68
	v_add_f32_e32 v169, 1.0, v130
	v_add_f32_e32 v130, 1.0, v131
	v_add_f32_e32 v131, 1.0, v133
	v_mul_f32_e32 v133, 0xbfb8aa3b, v71
	v_mul_f32_e32 v134, 0xbfb8aa3b, v67
	v_exp_f32_e32 v128, v128
	v_exp_f32_e32 v133, v133
	v_exp_f32_e32 v135, v134
	v_rcp_f32_e32 v134, v131
	v_add_f32_e32 v128, 1.0, v128
	v_add_f32_e32 v131, 1.0, v133
	v_add_f32_e32 v133, 1.0, v135
	v_rcp_f32_e32 v128, v128
	v_rcp_f32_e32 v129, v129
	v_rcp_f32_e32 v130, v130
	v_rcp_f32_e32 v131, v131
	v_rcp_f32_e32 v135, v133
	v_rcp_f32_e32 v133, v169
	v_pk_mul_f32 v[128:129], v[68:69], v[128:129]
	v_pk_mul_f32 v[130:131], v[70:71], v[130:131]
	v_pk_mul_f32 v[134:135], v[66:67], v[134:135]
	v_pk_mul_f32 v[132:133], v[64:65], v[132:133]
.LBB0_529:
	v_mov_b32_e32 v171, v145
	s_mul_i32 s31, s34, 0x50
	v_cvt_pk_bf16_f32 v128, v128, v129
	v_cvt_pk_bf16_f32 v129, v130, v131
	v_cvt_pk_bf16_f32 v130, v132, v133
	v_cvt_pk_bf16_f32 v131, v134, v135
	v_lshl_add_u64 v[132:133], v[172:173], 0, v[170:171]
	s_lshl_b32 s34, s31, 1
	s_mov_b32 s35, s1
	global_store_dwordx4 v[132:133], v[128:131], off
	v_lshl_add_u64 v[172:173], v[172:173], 0, s[34:35]
	v_mov_b64_e32 v[134:135], v[58:59]
	v_mov_b64_e32 v[130:131], v[62:63]
	s_and_b64 vcc, exec, s[4:5]
	v_mov_b64_e32 v[128:129], v[60:61]
	v_mov_b64_e32 v[132:133], v[56:57]
	s_cbranch_vccnz .LBB0_531
	v_mul_f32_e32 v129, 0xbfb8aa3b, v56
	v_mul_f32_e32 v130, 0xbfb8aa3b, v61
	v_exp_f32_e32 v129, v129
	v_exp_f32_e32 v130, v130
	v_mul_f32_e32 v131, 0xbfb8aa3b, v62
	v_mul_f32_e32 v133, 0xbfb8aa3b, v58
	v_add_f32_e32 v129, 1.0, v129
	v_rcp_f32_e32 v132, v129
	v_add_f32_e32 v129, 1.0, v130
	v_mul_f32_e32 v130, 0xbfb8aa3b, v57
	v_exp_f32_e32 v130, v130
	v_exp_f32_e32 v131, v131
	v_exp_f32_e32 v133, v133
	v_mul_f32_e32 v128, 0xbfb8aa3b, v60
	v_add_f32_e32 v169, 1.0, v130
	v_add_f32_e32 v130, 1.0, v131
	v_add_f32_e32 v131, 1.0, v133
	v_mul_f32_e32 v133, 0xbfb8aa3b, v63
	v_mul_f32_e32 v134, 0xbfb8aa3b, v59
	v_exp_f32_e32 v128, v128
	v_exp_f32_e32 v133, v133
	v_exp_f32_e32 v135, v134
	v_rcp_f32_e32 v134, v131
	v_add_f32_e32 v128, 1.0, v128
	v_add_f32_e32 v131, 1.0, v133
	v_add_f32_e32 v133, 1.0, v135
	v_rcp_f32_e32 v128, v128
	v_rcp_f32_e32 v129, v129
	v_rcp_f32_e32 v130, v130
	v_rcp_f32_e32 v131, v131
	v_rcp_f32_e32 v135, v133
	v_rcp_f32_e32 v133, v169
	v_pk_mul_f32 v[128:129], v[60:61], v[128:129]
	v_pk_mul_f32 v[130:131], v[62:63], v[130:131]
	v_pk_mul_f32 v[134:135], v[58:59], v[134:135]
	v_pk_mul_f32 v[132:133], v[56:57], v[132:133]
.LBB0_531:
	v_cvt_pk_bf16_f32 v128, v128, v129
	v_cvt_pk_bf16_f32 v129, v130, v131
	v_cvt_pk_bf16_f32 v130, v132, v133
	v_cvt_pk_bf16_f32 v131, v134, v135
	v_lshl_add_u64 v[132:133], v[172:173], 0, v[144:145]
	global_store_dwordx4 v[132:133], v[128:131], off
	v_mov_b64_e32 v[134:135], v[50:51]
	s_and_b64 vcc, exec, s[4:5]
	v_mov_b64_e32 v[130:131], v[54:55]
	v_mov_b64_e32 v[128:129], v[52:53]
	v_mov_b64_e32 v[132:133], v[48:49]
	s_cbranch_vccnz .LBB0_533
	v_mul_f32_e32 v129, 0xbfb8aa3b, v48
	v_mul_f32_e32 v130, 0xbfb8aa3b, v53
	v_exp_f32_e32 v129, v129
	v_exp_f32_e32 v130, v130
	v_mul_f32_e32 v131, 0xbfb8aa3b, v54
	v_mul_f32_e32 v133, 0xbfb8aa3b, v50
	v_add_f32_e32 v129, 1.0, v129
	v_rcp_f32_e32 v132, v129
	v_add_f32_e32 v129, 1.0, v130
	v_mul_f32_e32 v130, 0xbfb8aa3b, v49
	v_exp_f32_e32 v130, v130
	v_exp_f32_e32 v131, v131
	v_exp_f32_e32 v133, v133
	v_mul_f32_e32 v128, 0xbfb8aa3b, v52
	v_add_f32_e32 v169, 1.0, v130
	v_add_f32_e32 v130, 1.0, v131
	v_add_f32_e32 v131, 1.0, v133
	v_mul_f32_e32 v133, 0xbfb8aa3b, v55
	v_mul_f32_e32 v134, 0xbfb8aa3b, v51
	v_exp_f32_e32 v128, v128
	v_exp_f32_e32 v133, v133
	v_exp_f32_e32 v135, v134
	v_rcp_f32_e32 v134, v131
	v_add_f32_e32 v128, 1.0, v128
	v_add_f32_e32 v131, 1.0, v133
	v_add_f32_e32 v133, 1.0, v135
	v_rcp_f32_e32 v128, v128
	v_rcp_f32_e32 v129, v129
	v_rcp_f32_e32 v130, v130
	v_rcp_f32_e32 v131, v131
	v_rcp_f32_e32 v135, v133
	v_rcp_f32_e32 v133, v169
	v_pk_mul_f32 v[128:129], v[52:53], v[128:129]
	v_pk_mul_f32 v[130:131], v[54:55], v[130:131]
	v_pk_mul_f32 v[134:135], v[50:51], v[134:135]
	v_pk_mul_f32 v[132:133], v[48:49], v[132:133]
.LBB0_533:
	v_mov_b32_e32 v171, v145
	v_cvt_pk_bf16_f32 v128, v128, v129
	v_cvt_pk_bf16_f32 v129, v130, v131
	v_cvt_pk_bf16_f32 v130, v132, v133
	v_cvt_pk_bf16_f32 v131, v134, v135
	v_lshl_add_u64 v[132:133], v[172:173], 0, v[170:171]
	global_store_dwordx4 v[132:133], v[128:131], off
	v_lshl_add_u64 v[172:173], v[172:173], 0, s[0:1]
	v_mov_b64_e32 v[134:135], v[42:43]
	v_mov_b64_e32 v[130:131], v[46:47]
	s_and_b64 vcc, exec, s[4:5]
	v_mov_b64_e32 v[128:129], v[44:45]
	v_mov_b64_e32 v[132:133], v[40:41]
	s_cbranch_vccnz .LBB0_535
	v_mul_f32_e32 v129, 0xbfb8aa3b, v40
	v_mul_f32_e32 v130, 0xbfb8aa3b, v45
	v_exp_f32_e32 v129, v129
	v_exp_f32_e32 v130, v130
	v_mul_f32_e32 v131, 0xbfb8aa3b, v46
	v_mul_f32_e32 v133, 0xbfb8aa3b, v42
	v_add_f32_e32 v129, 1.0, v129
	v_rcp_f32_e32 v132, v129
	v_add_f32_e32 v129, 1.0, v130
	v_mul_f32_e32 v130, 0xbfb8aa3b, v41
	v_exp_f32_e32 v130, v130
	v_exp_f32_e32 v131, v131
	v_exp_f32_e32 v133, v133
	v_mul_f32_e32 v128, 0xbfb8aa3b, v44
	v_add_f32_e32 v169, 1.0, v130
	v_add_f32_e32 v130, 1.0, v131
	v_add_f32_e32 v131, 1.0, v133
	v_mul_f32_e32 v133, 0xbfb8aa3b, v47
	v_mul_f32_e32 v134, 0xbfb8aa3b, v43
	v_exp_f32_e32 v128, v128
	v_exp_f32_e32 v133, v133
	v_exp_f32_e32 v135, v134
	v_rcp_f32_e32 v134, v131
	v_add_f32_e32 v128, 1.0, v128
	v_add_f32_e32 v131, 1.0, v133
	v_add_f32_e32 v133, 1.0, v135
	v_rcp_f32_e32 v128, v128
	v_rcp_f32_e32 v129, v129
	v_rcp_f32_e32 v130, v130
	v_rcp_f32_e32 v131, v131
	v_rcp_f32_e32 v135, v133
	v_rcp_f32_e32 v133, v169
	v_pk_mul_f32 v[128:129], v[44:45], v[128:129]
	v_pk_mul_f32 v[130:131], v[46:47], v[130:131]
	v_pk_mul_f32 v[134:135], v[42:43], v[134:135]
	v_pk_mul_f32 v[132:133], v[40:41], v[132:133]
.LBB0_535:
	v_cvt_pk_bf16_f32 v128, v128, v129
	v_cvt_pk_bf16_f32 v129, v130, v131
	v_cvt_pk_bf16_f32 v130, v132, v133
	v_cvt_pk_bf16_f32 v131, v134, v135
	v_lshl_add_u64 v[132:133], v[172:173], 0, v[144:145]
	global_store_dwordx4 v[132:133], v[128:131], off
	v_mov_b64_e32 v[134:135], v[34:35]
	s_and_b64 vcc, exec, s[4:5]
	v_mov_b64_e32 v[130:131], v[38:39]
	v_mov_b64_e32 v[128:129], v[36:37]
	v_mov_b64_e32 v[132:133], v[32:33]
	s_cbranch_vccnz .LBB0_537
	v_mul_f32_e32 v129, 0xbfb8aa3b, v32
	v_mul_f32_e32 v130, 0xbfb8aa3b, v37
	v_exp_f32_e32 v129, v129
	v_exp_f32_e32 v130, v130
	v_mul_f32_e32 v131, 0xbfb8aa3b, v38
	v_mul_f32_e32 v133, 0xbfb8aa3b, v34
	v_add_f32_e32 v129, 1.0, v129
	v_rcp_f32_e32 v132, v129
	v_add_f32_e32 v129, 1.0, v130
	v_mul_f32_e32 v130, 0xbfb8aa3b, v33
	v_exp_f32_e32 v130, v130
	v_exp_f32_e32 v131, v131
	v_exp_f32_e32 v133, v133
	v_mul_f32_e32 v128, 0xbfb8aa3b, v36
	v_add_f32_e32 v169, 1.0, v130
	v_add_f32_e32 v130, 1.0, v131
	v_add_f32_e32 v131, 1.0, v133
	v_mul_f32_e32 v133, 0xbfb8aa3b, v39
	v_mul_f32_e32 v134, 0xbfb8aa3b, v35
	v_exp_f32_e32 v128, v128
	v_exp_f32_e32 v133, v133
	v_exp_f32_e32 v135, v134
	v_rcp_f32_e32 v134, v131
	v_add_f32_e32 v128, 1.0, v128
	v_add_f32_e32 v131, 1.0, v133
	v_add_f32_e32 v133, 1.0, v135
	v_rcp_f32_e32 v128, v128
	v_rcp_f32_e32 v129, v129
	v_rcp_f32_e32 v130, v130
	v_rcp_f32_e32 v131, v131
	v_rcp_f32_e32 v135, v133
	v_rcp_f32_e32 v133, v169
	v_pk_mul_f32 v[128:129], v[36:37], v[128:129]
	v_pk_mul_f32 v[130:131], v[38:39], v[130:131]
	v_pk_mul_f32 v[134:135], v[34:35], v[134:135]
	v_pk_mul_f32 v[132:133], v[32:33], v[132:133]
.LBB0_537:
	v_mov_b32_e32 v171, v145
	v_cvt_pk_bf16_f32 v128, v128, v129
	v_cvt_pk_bf16_f32 v129, v130, v131
	v_cvt_pk_bf16_f32 v130, v132, v133
	v_cvt_pk_bf16_f32 v131, v134, v135
	v_lshl_add_u64 v[132:133], v[172:173], 0, v[170:171]
	global_store_dwordx4 v[132:133], v[128:131], off
	v_lshl_add_u64 v[172:173], v[172:173], 0, s[0:1]
	v_mov_b64_e32 v[134:135], v[26:27]
	v_mov_b64_e32 v[130:131], v[30:31]
	s_and_b64 vcc, exec, s[4:5]
	v_mov_b64_e32 v[128:129], v[28:29]
	v_mov_b64_e32 v[132:133], v[24:25]
	s_cbranch_vccnz .LBB0_539
	v_mul_f32_e32 v129, 0xbfb8aa3b, v24
	v_mul_f32_e32 v130, 0xbfb8aa3b, v29
	v_exp_f32_e32 v129, v129
	v_exp_f32_e32 v130, v130
	v_mul_f32_e32 v131, 0xbfb8aa3b, v30
	v_mul_f32_e32 v133, 0xbfb8aa3b, v26
	v_add_f32_e32 v129, 1.0, v129
	v_rcp_f32_e32 v132, v129
	v_add_f32_e32 v129, 1.0, v130
	v_mul_f32_e32 v130, 0xbfb8aa3b, v25
	v_exp_f32_e32 v130, v130
	v_exp_f32_e32 v131, v131
	v_exp_f32_e32 v133, v133
	v_mul_f32_e32 v128, 0xbfb8aa3b, v28
	v_add_f32_e32 v169, 1.0, v130
	v_add_f32_e32 v130, 1.0, v131
	v_add_f32_e32 v131, 1.0, v133
	v_mul_f32_e32 v133, 0xbfb8aa3b, v31
	v_mul_f32_e32 v134, 0xbfb8aa3b, v27
	v_exp_f32_e32 v128, v128
	v_exp_f32_e32 v133, v133
	v_exp_f32_e32 v135, v134
	v_rcp_f32_e32 v134, v131
	v_add_f32_e32 v128, 1.0, v128
	v_add_f32_e32 v131, 1.0, v133
	v_add_f32_e32 v133, 1.0, v135
	v_rcp_f32_e32 v128, v128
	v_rcp_f32_e32 v129, v129
	v_rcp_f32_e32 v130, v130
	v_rcp_f32_e32 v131, v131
	v_rcp_f32_e32 v135, v133
	v_rcp_f32_e32 v133, v169
	v_pk_mul_f32 v[128:129], v[28:29], v[128:129]
	v_pk_mul_f32 v[130:131], v[30:31], v[130:131]
	v_pk_mul_f32 v[134:135], v[26:27], v[134:135]
	v_pk_mul_f32 v[132:133], v[24:25], v[132:133]
.LBB0_539:
	v_cvt_pk_bf16_f32 v128, v128, v129
	v_cvt_pk_bf16_f32 v129, v130, v131
	v_cvt_pk_bf16_f32 v130, v132, v133
	v_cvt_pk_bf16_f32 v131, v134, v135
	v_lshl_add_u64 v[132:133], v[172:173], 0, v[144:145]
	global_store_dwordx4 v[132:133], v[128:131], off
	v_mov_b64_e32 v[134:135], v[18:19]
	s_and_b64 vcc, exec, s[4:5]
	v_mov_b64_e32 v[130:131], v[22:23]
	v_mov_b64_e32 v[128:129], v[20:21]
	v_mov_b64_e32 v[132:133], v[16:17]
	s_cbranch_vccnz .LBB0_541
	v_mul_f32_e32 v129, 0xbfb8aa3b, v16
	v_mul_f32_e32 v130, 0xbfb8aa3b, v21
	v_exp_f32_e32 v129, v129
	v_exp_f32_e32 v130, v130
	v_mul_f32_e32 v131, 0xbfb8aa3b, v22
	v_mul_f32_e32 v133, 0xbfb8aa3b, v18
	v_add_f32_e32 v129, 1.0, v129
	v_rcp_f32_e32 v132, v129
	v_add_f32_e32 v129, 1.0, v130
	v_mul_f32_e32 v130, 0xbfb8aa3b, v17
	v_exp_f32_e32 v130, v130
	v_exp_f32_e32 v131, v131
	v_exp_f32_e32 v133, v133
	v_mul_f32_e32 v128, 0xbfb8aa3b, v20
	v_add_f32_e32 v169, 1.0, v130
	v_add_f32_e32 v130, 1.0, v131
	v_add_f32_e32 v131, 1.0, v133
	v_mul_f32_e32 v133, 0xbfb8aa3b, v23
	v_mul_f32_e32 v134, 0xbfb8aa3b, v19
	v_exp_f32_e32 v128, v128
	v_exp_f32_e32 v133, v133
	v_exp_f32_e32 v135, v134
	v_rcp_f32_e32 v134, v131
	v_add_f32_e32 v128, 1.0, v128
	v_add_f32_e32 v131, 1.0, v133
	v_add_f32_e32 v133, 1.0, v135
	v_rcp_f32_e32 v128, v128
	v_rcp_f32_e32 v129, v129
	v_rcp_f32_e32 v130, v130
	v_rcp_f32_e32 v131, v131
	v_rcp_f32_e32 v135, v133
	v_rcp_f32_e32 v133, v169
	v_pk_mul_f32 v[128:129], v[20:21], v[128:129]
	v_pk_mul_f32 v[130:131], v[22:23], v[130:131]
	v_pk_mul_f32 v[134:135], v[18:19], v[134:135]
	v_pk_mul_f32 v[132:133], v[16:17], v[132:133]
.LBB0_541:
	v_mov_b32_e32 v171, v145
	v_cvt_pk_bf16_f32 v128, v128, v129
	v_cvt_pk_bf16_f32 v129, v130, v131
	v_cvt_pk_bf16_f32 v130, v132, v133
	v_cvt_pk_bf16_f32 v131, v134, v135
	v_lshl_add_u64 v[132:133], v[172:173], 0, v[170:171]
	global_store_dwordx4 v[132:133], v[128:131], off
	v_lshl_add_u64 v[172:173], v[172:173], 0, s[0:1]
	v_mov_b64_e32 v[134:135], v[10:11]
	v_mov_b64_e32 v[130:131], v[14:15]
	s_and_b64 vcc, exec, s[4:5]
	v_mov_b64_e32 v[128:129], v[12:13]
	v_mov_b64_e32 v[132:133], v[8:9]
	s_cbranch_vccnz .LBB0_543
	v_mul_f32_e32 v129, 0xbfb8aa3b, v8
	v_mul_f32_e32 v130, 0xbfb8aa3b, v13
	v_exp_f32_e32 v129, v129
	v_exp_f32_e32 v130, v130
	v_mul_f32_e32 v131, 0xbfb8aa3b, v14
	v_mul_f32_e32 v133, 0xbfb8aa3b, v10
	v_add_f32_e32 v129, 1.0, v129
	v_rcp_f32_e32 v132, v129
	v_add_f32_e32 v129, 1.0, v130
	v_mul_f32_e32 v130, 0xbfb8aa3b, v9
	v_exp_f32_e32 v130, v130
	v_exp_f32_e32 v131, v131
	v_exp_f32_e32 v133, v133
	v_mul_f32_e32 v128, 0xbfb8aa3b, v12
	v_add_f32_e32 v169, 1.0, v130
	v_add_f32_e32 v130, 1.0, v131
	v_add_f32_e32 v131, 1.0, v133
	v_mul_f32_e32 v133, 0xbfb8aa3b, v15
	v_mul_f32_e32 v134, 0xbfb8aa3b, v11
	v_exp_f32_e32 v128, v128
	v_exp_f32_e32 v133, v133
	v_exp_f32_e32 v135, v134
	v_rcp_f32_e32 v134, v131
	v_add_f32_e32 v128, 1.0, v128
	v_add_f32_e32 v131, 1.0, v133
	v_add_f32_e32 v133, 1.0, v135
	v_rcp_f32_e32 v128, v128
	v_rcp_f32_e32 v129, v129
	v_rcp_f32_e32 v130, v130
	v_rcp_f32_e32 v131, v131
	v_rcp_f32_e32 v135, v133
	v_rcp_f32_e32 v133, v169
	v_pk_mul_f32 v[128:129], v[12:13], v[128:129]
	v_pk_mul_f32 v[130:131], v[14:15], v[130:131]
	v_pk_mul_f32 v[134:135], v[10:11], v[134:135]
	v_pk_mul_f32 v[132:133], v[8:9], v[132:133]
.LBB0_543:
	v_cvt_pk_bf16_f32 v128, v128, v129
	v_cvt_pk_bf16_f32 v129, v130, v131
	v_cvt_pk_bf16_f32 v130, v132, v133
	v_cvt_pk_bf16_f32 v131, v134, v135
	v_lshl_add_u64 v[132:133], v[172:173], 0, v[144:145]
	global_store_dwordx4 v[132:133], v[128:131], off
	v_mov_b64_e32 v[134:135], v[2:3]
	s_and_b64 vcc, exec, s[4:5]
	v_mov_b64_e32 v[130:131], v[6:7]
	v_mov_b64_e32 v[128:129], v[4:5]
	v_mov_b64_e32 v[132:133], v[0:1]
	s_cbranch_vccnz .LBB0_545
	v_mul_f32_e32 v129, 0xbfb8aa3b, v0
	v_mul_f32_e32 v130, 0xbfb8aa3b, v5
	v_exp_f32_e32 v129, v129
	v_exp_f32_e32 v130, v130
	v_mul_f32_e32 v131, 0xbfb8aa3b, v6
	v_mul_f32_e32 v133, 0xbfb8aa3b, v2
	v_add_f32_e32 v129, 1.0, v129
	v_rcp_f32_e32 v132, v129
	v_add_f32_e32 v129, 1.0, v130
	v_mul_f32_e32 v130, 0xbfb8aa3b, v1
	v_exp_f32_e32 v130, v130
	v_exp_f32_e32 v131, v131
	v_exp_f32_e32 v133, v133
	v_mul_f32_e32 v128, 0xbfb8aa3b, v4
	v_add_f32_e32 v144, 1.0, v130
	v_add_f32_e32 v130, 1.0, v131
	v_add_f32_e32 v131, 1.0, v133
	v_mul_f32_e32 v133, 0xbfb8aa3b, v7
	v_mul_f32_e32 v134, 0xbfb8aa3b, v3
	v_exp_f32_e32 v128, v128
	v_exp_f32_e32 v133, v133
	v_exp_f32_e32 v135, v134
	v_rcp_f32_e32 v134, v131
	v_add_f32_e32 v128, 1.0, v128
	v_add_f32_e32 v131, 1.0, v133
	v_add_f32_e32 v133, 1.0, v135
	v_rcp_f32_e32 v128, v128
	v_rcp_f32_e32 v129, v129
	v_rcp_f32_e32 v130, v130
	v_rcp_f32_e32 v131, v131
	v_rcp_f32_e32 v135, v133
	v_rcp_f32_e32 v133, v144
	v_pk_mul_f32 v[128:129], v[4:5], v[128:129]
	v_pk_mul_f32 v[130:131], v[6:7], v[130:131]
	v_pk_mul_f32 v[134:135], v[2:3], v[134:135]
	v_pk_mul_f32 v[132:133], v[0:1], v[132:133]
.LBB0_545:
	v_mov_b32_e32 v171, v145
	v_cvt_pk_bf16_f32 v128, v128, v129
	v_cvt_pk_bf16_f32 v129, v130, v131
	v_cvt_pk_bf16_f32 v130, v132, v133
	v_cvt_pk_bf16_f32 v131, v134, v135
	v_lshl_add_u64 v[132:133], v[172:173], 0, v[170:171]
	s_mov_b32 s35, s1
	global_store_dwordx4 v[132:133], v[128:131], off
	s_nop 1
	v_lshl_add_u64 v[128:129], v[172:173], 0, s[34:35]

.LBB0_572:
	s_or_b64 exec, exec, s[26:27]
	s_mul_i32 s14, s90, 0x4100
	s_add_i32 s24, s14, 0
	s_sub_i32 s14, s86, s30
	s_lshl_b32 s33, s14, 3
	s_ff1_i32_b32 s14, s21
	s_and_b32 s21, s36, 0xffff
	v_lshlrev_b32_e32 v1, 2, v147
	v_bfe_u32 v131, v147, 4, 2
	s_lshr_b32 s14, s21, s14
	v_and_b32_e32 v130, 28, v1
	v_lshl_or_b32 v1, s14, 6, v131
	v_mul_hi_u32_u24_e32 v3, s20, v1
	v_mul_u32_u24_e32 v2, s20, v1
	v_lshl_add_u64 v[2:3], v[2:3], 2, s[22:23]
	v_add_u32_e32 v128, v0, v130
	v_mov_b32_e32 v129, 0
	s_mov_b32 s15, 0
	v_lshl_add_u64 v[60:61], v[128:129], 2, v[2:3]
	s_mul_i32 s14, s20, 0xf0
	v_lshl_add_u64 v[16:17], v[60:61], 0, s[14:15]
	s_lshl_b32 s14, s20, 4
	s_sub_u32 s20, 0, s14
	s_subb_u32 s21, 0, 0
	v_lshl_add_u64 v[0:1], v[16:17], 0, s[20:21]
	v_lshl_add_u64 v[8:9], v[0:1], 0, s[20:21]
	global_load_dwordx4 v[0:3], v[0:1], off nt
	s_nop 0
	global_load_dwordx4 v[4:7], v[8:9], off nt
	v_lshl_add_u64 v[8:9], v[8:9], 0, s[20:21]
	v_lshl_add_u64 v[18:19], v[8:9], 0, s[20:21]
	global_load_dwordx4 v[8:11], v[8:9], off nt
	s_nop 0
	global_load_dwordx4 v[12:15], v[18:19], off nt
	v_lshl_add_u64 v[18:19], v[18:19], 0, s[20:21]
	v_lshl_add_u64 v[28:29], v[18:19], 0, s[20:21]
	global_load_dwordx4 v[20:23], v[18:19], off nt
	global_load_dwordx4 v[24:27], v[28:29], off nt
	v_lshl_add_u64 v[18:19], v[28:29], 0, s[20:21]
	global_load_dwordx4 v[28:31], v[18:19], off nt
	v_lshl_add_u64 v[18:19], v[18:19], 0, s[20:21]
	global_load_dwordx4 v[32:35], v[18:19], off nt
	v_lshl_add_u64 v[18:19], v[18:19], 0, s[20:21]
	global_load_dwordx4 v[36:39], v[18:19], off nt
	v_lshl_add_u64 v[18:19], v[18:19], 0, s[20:21]
	global_load_dwordx4 v[40:43], v[18:19], off nt
	v_lshl_add_u64 v[18:19], v[18:19], 0, s[20:21]
	global_load_dwordx4 v[44:47], v[18:19], off nt
	v_lshl_add_u64 v[18:19], v[18:19], 0, s[20:21]
	global_load_dwordx4 v[48:51], v[18:19], off nt
	v_lshl_add_u64 v[18:19], v[18:19], 0, s[20:21]
	global_load_dwordx4 v[52:55], v[18:19], off nt
	v_lshl_add_u64 v[18:19], v[18:19], 0, s[20:21]
	global_load_dwordx4 v[56:59], v[18:19], off nt
	s_nop 0
	global_load_dwordx4 v[16:19], v[16:17], off nt
	s_nop 0
	global_load_dwordx4 v[60:63], v[60:61], off nt
	v_lshlrev_b32_e32 v64, 4, v147
	v_and_b32_e32 v64, 0xf0, v64
	v_add_u32_e32 v65, s24, v64
	v_lshlrev_b32_e32 v64, 3, v147
	v_readlane_b32 s20, v255, 23
	v_bfe_u32 v132, v147, 3, 3
	v_and_b32_e32 v64, 56, v64
	s_add_i32 s14, s90, s20
	s_lshl_b32 s20, s30, 4
	v_mul_u32_u24_e32 v66, 0x104, v131
	v_mul_u32_u24_e32 v67, 0x104, v64
	v_lshlrev_b32_e32 v68, 2, v132
	s_sub_i32 s38, s14, s20
	s_lshl_b32 s14, s30, 3
	v_add3_u32 v133, s24, v67, v68
	v_or_b32_e32 v134, 8, v132
	v_or_b32_e32 v135, 16, v132
	v_or_b32_e32 v136, 24, v132
	v_or_b32_e32 v137, 32, v132
	v_or_b32_e32 v138, 40, v132
	v_or_b32_e32 v139, 48, v132
	v_or_b32_e32 v140, 56, v132
	s_lshl_b32 s37, s93, 3
	v_readlane_b32 s21, v255, 24
	s_sub_i32 s39, s90, s14
	v_add_u32_e32 v141, v65, v66
	v_lshlrev_b32_e32 v128, 1, v64
	s_waitcnt vmcnt(0)
	s_branch .LBB0_575

.LBB0_574:
	s_ashr_i32 s14, s42, 31
	s_lshr_b32 s14, s14, 26
	s_add_i32 s14, s42, s14
	ds_write2_b32 v141, v60, v61 offset1:1
	ds_write2_b32 v141, v62, v63 offset0:2 offset1:3
	v_add_u32_e32 v60, 0x410, v141
	s_ashr_i32 s14, s14, 6
	ds_write2_b32 v60, v56, v57 offset1:1
	v_add_u32_e32 v56, 0x418, v141
	s_abs_i32 s22, s14
	ds_write2_b32 v56, v58, v59 offset1:1
	v_add_u32_e32 v56, 0x820, v141
	v_cvt_f32_u32_e32 v142, s22
	ds_write2_b32 v56, v52, v53 offset1:1
	v_add_u32_e32 v52, 0x828, v141
	ds_write2_b32 v52, v54, v55 offset1:1
	v_add_u32_e32 v52, 0xc30, v141
	ds_write2_b32 v52, v48, v49 offset1:1
	v_add_u32_e32 v48, 0xc38, v141
	ds_write2_b32 v48, v50, v51 offset1:1
	v_add_u32_e32 v48, 0x1040, v141
	v_rcp_iflag_f32_e32 v142, v142
	ds_write2_b32 v48, v44, v45 offset1:1
	v_add_u32_e32 v44, 0x1048, v141
	ds_write2_b32 v44, v46, v47 offset1:1
	v_add_u32_e32 v44, 0x1450, v141
	ds_write2_b32 v44, v40, v41 offset1:1
	v_add_u32_e32 v40, 0x1458, v141
	ds_write2_b32 v40, v42, v43 offset1:1
	v_add_u32_e32 v40, 0x1860, v141
	v_mul_f32_e32 v61, 0x4f7ffffe, v142
	ds_write2_b32 v40, v36, v37 offset1:1
	v_add_u32_e32 v36, 0x1868, v141
	v_cvt_u32_f32_e32 v61, v61
	ds_write2_b32 v36, v38, v39 offset1:1
	v_add_u32_e32 v36, 0x1c70, v141
	ds_write2_b32 v36, v32, v33 offset1:1
	v_add_u32_e32 v32, 0x1c78, v141
	ds_write2_b32 v32, v34, v35 offset1:1
	v_add_u32_e32 v32, 0x2080, v141
	ds_write2_b32 v32, v28, v29 offset1:1
	v_add_u32_e32 v28, 0x2088, v141
	s_sub_i32 s25, 0, s22
	v_readfirstlane_b32 s26, v61
	ds_write2_b32 v28, v30, v31 offset1:1
	v_add_u32_e32 v28, 0x2490, v141
	s_mul_i32 s25, s25, s26
	ds_write2_b32 v28, v24, v25 offset1:1
	v_add_u32_e32 v24, 0x2498, v141
	s_mul_hi_u32 s25, s26, s25
	ds_write2_b32 v24, v26, v27 offset1:1
	v_add_u32_e32 v24, 0x28a0, v141
	s_abs_i32 s23, s36
	s_add_i32 s26, s26, s25
	ds_write2_b32 v24, v20, v21 offset1:1
	v_add_u32_e32 v20, 0x28a8, v141
	s_mul_hi_u32 s25, s23, s26
	ds_write2_b32 v20, v22, v23 offset1:1
	v_add_u32_e32 v20, 0x2cb0, v141
	s_mul_i32 s26, s25, s22
	ds_write2_b32 v20, v12, v13 offset1:1
	v_add_u32_e32 v12, 0x2cb8, v141
	s_xor_b32 s24, s36, s14
	s_sub_i32 s23, s23, s26
	ds_write2_b32 v12, v14, v15 offset1:1
	v_add_u32_e32 v12, 0x30c0, v141
	s_ashr_i32 s24, s24, 31
	s_add_i32 s27, s25, 1
	s_sub_i32 s26, s23, s22
	ds_write2_b32 v12, v8, v9 offset1:1
	v_add_u32_e32 v8, 0x30c8, v141
	s_cmp_ge_u32 s23, s22
	ds_write2_b32 v8, v10, v11 offset1:1
	v_add_u32_e32 v8, 0x34d0, v141
	s_cselect_b32 s25, s27, s25
	ds_write2_b32 v8, v4, v5 offset1:1
	v_add_u32_e32 v4, 0x34d8, v141
	s_cselect_b32 s23, s26, s23
	s_add_i32 s26, s25, 1
	ds_write2_b32 v4, v6, v7 offset1:1
	v_add_u32_e32 v4, 0x38e0, v141
	s_cmp_ge_u32 s23, s22
	ds_write2_b32 v4, v0, v1 offset1:1
	v_add_u32_e32 v0, 0x38e8, v141
	s_cselect_b32 s22, s26, s25
	ds_write2_b32 v0, v2, v3 offset1:1
	v_add_u32_e32 v0, 0x3cf0, v141
	s_xor_b32 s22, s22, s24
	ds_write2_b32 v0, v16, v17 offset1:1
	v_add_u32_e32 v0, 0x3cf8, v141
	s_sub_i32 s23, s22, s24
	ds_write2_b32 v0, v18, v19 offset1:1
	s_lshl_b32 s22, s23, 6
	s_mul_i32 s23, s23, s14
	s_waitcnt lgkmcnt(0)
	v_add_u32_e32 v24, 0x400, v133
	s_sub_i32 s14, s36, s23
	s_ashr_i32 s23, s22, 31
	ds_read2_b32 v[4:5], v133 offset0:65 offset1:73
	ds_read2_b32 v[6:7], v133 offset1:8
	ds_read2_b32 v[8:9], v133 offset0:130 offset1:138
	ds_read2_b32 v[10:11], v133 offset0:195 offset1:203
	ds_read2_b32 v[12:13], v24 offset0:4 offset1:12
	ds_read2_b32 v[14:15], v24 offset0:69 offset1:77
	ds_read2_b32 v[16:17], v24 offset0:134 offset1:142
	ds_read2_b32 v[18:19], v24 offset0:199 offset1:207
	s_lshl_b32 s14, s14, 6
	s_lshl_b64 s[22:23], s[22:23], 1
	s_add_u32 s18, s18, s22
	v_or_b32_e32 v22, s14, v132
	s_addc_u32 s19, s19, s23
	v_ashrrev_i32_e32 v23, 31, v22
	v_lshl_add_u64 v[20:21], s[18:19], 0, v[128:129]
	v_lshlrev_b64 v[22:23], 12, v[22:23]
	s_waitcnt lgkmcnt(6)
	v_cvt_pk_bf16_f32 v0, v6, v4
	s_waitcnt lgkmcnt(4)
	v_cvt_pk_bf16_f32 v1, v8, v10
	s_waitcnt lgkmcnt(2)
	v_cvt_pk_bf16_f32 v2, v12, v14
	s_waitcnt lgkmcnt(0)
	v_cvt_pk_bf16_f32 v3, v16, v18
	v_lshl_add_u64 v[22:23], v[20:21], 0, v[22:23]
	v_or_b32_e32 v4, s14, v134
	global_store_dwordx4 v[22:23], v[0:3], off
	s_add_i32 s39, s39, s33
	s_add_i32 s38, s38, s33
	v_cvt_pk_bf16_f32 v0, v7, v5
	v_ashrrev_i32_e32 v5, 31, v4
	v_cvt_pk_bf16_f32 v1, v9, v11
	v_cvt_pk_bf16_f32 v2, v13, v15
	v_cvt_pk_bf16_f32 v3, v17, v19
	v_lshlrev_b64 v[4:5], 12, v[4:5]
	ds_read2_b32 v[6:7], v133 offset0:81 offset1:89
	ds_read2_b32 v[8:9], v133 offset0:16 offset1:24
	ds_read2_b32 v[10:11], v133 offset0:146 offset1:154
	ds_read2_b32 v[12:13], v133 offset0:211 offset1:219
	ds_read2_b32 v[14:15], v24 offset0:20 offset1:28
	ds_read2_b32 v[16:17], v24 offset0:85 offset1:93
	ds_read2_b32 v[18:19], v24 offset0:150 offset1:158
	ds_read2_b32 v[22:23], v24 offset0:215 offset1:223
	v_lshl_add_u64 v[4:5], v[20:21], 0, v[4:5]
	global_store_dwordx4 v[4:5], v[0:3], off
	v_or_b32_e32 v4, s14, v135
	v_ashrrev_i32_e32 v5, 31, v4
	v_lshlrev_b64 v[4:5], 12, v[4:5]
	s_waitcnt lgkmcnt(6)
	v_cvt_pk_bf16_f32 v0, v8, v6
	s_waitcnt lgkmcnt(4)
	v_cvt_pk_bf16_f32 v1, v10, v12
	s_waitcnt lgkmcnt(2)
	v_cvt_pk_bf16_f32 v2, v14, v16
	s_waitcnt lgkmcnt(0)
	v_cvt_pk_bf16_f32 v3, v18, v22
	v_lshl_add_u64 v[4:5], v[20:21], 0, v[4:5]
	global_store_dwordx4 v[4:5], v[0:3], off
	v_or_b32_e32 v4, s14, v136
	v_ashrrev_i32_e32 v5, 31, v4
	v_cvt_pk_bf16_f32 v0, v9, v7
	v_cvt_pk_bf16_f32 v1, v11, v13
	v_cvt_pk_bf16_f32 v2, v15, v17
	v_cvt_pk_bf16_f32 v3, v19, v23
	v_lshlrev_b64 v[4:5], 12, v[4:5]
	ds_read2_b32 v[6:7], v133 offset0:32 offset1:40
	ds_read2_b32 v[8:9], v133 offset0:97 offset1:105
	ds_read2_b32 v[10:11], v133 offset0:162 offset1:170
	ds_read2_b32 v[12:13], v133 offset0:227 offset1:235
	ds_read2_b32 v[14:15], v24 offset0:36 offset1:44
	ds_read2_b32 v[16:17], v24 offset0:101 offset1:109
	ds_read2_b32 v[18:19], v24 offset0:166 offset1:174
	ds_read2_b32 v[22:23], v24 offset0:231 offset1:239
	v_lshl_add_u64 v[4:5], v[20:21], 0, v[4:5]
	global_store_dwordx4 v[4:5], v[0:3], off
	v_or_b32_e32 v4, s14, v137
	v_ashrrev_i32_e32 v5, 31, v4
	v_lshlrev_b64 v[4:5], 12, v[4:5]
	s_waitcnt lgkmcnt(6)
	v_cvt_pk_bf16_f32 v0, v6, v8
	s_waitcnt lgkmcnt(4)
	v_cvt_pk_bf16_f32 v1, v10, v12
	s_waitcnt lgkmcnt(2)
	v_cvt_pk_bf16_f32 v2, v14, v16
	s_waitcnt lgkmcnt(0)
	v_cvt_pk_bf16_f32 v3, v18, v22
	v_lshl_add_u64 v[4:5], v[20:21], 0, v[4:5]
	global_store_dwordx4 v[4:5], v[0:3], off
	v_or_b32_e32 v4, s14, v138
	v_ashrrev_i32_e32 v5, 31, v4
	v_cvt_pk_bf16_f32 v0, v7, v9
	v_cvt_pk_bf16_f32 v1, v11, v13
	v_cvt_pk_bf16_f32 v2, v15, v17
	v_cvt_pk_bf16_f32 v3, v19, v23
	v_lshlrev_b64 v[4:5], 12, v[4:5]
	ds_read2_b32 v[6:7], v133 offset0:48 offset1:56
	ds_read2_b32 v[8:9], v133 offset0:113 offset1:121
	ds_read2_b32 v[10:11], v133 offset0:178 offset1:186
	ds_read2_b32 v[12:13], v133 offset0:243 offset1:251
	ds_read2_b32 v[14:15], v24 offset0:52 offset1:60
	ds_read2_b32 v[16:17], v24 offset0:117 offset1:125
	ds_read2_b32 v[18:19], v24 offset0:182 offset1:190
	ds_read2_b32 v[22:23], v24 offset0:247 offset1:255
	v_lshl_add_u64 v[4:5], v[20:21], 0, v[4:5]
	global_store_dwordx4 v[4:5], v[0:3], off
	v_or_b32_e32 v4, s14, v139
	v_ashrrev_i32_e32 v5, 31, v4
	v_lshlrev_b64 v[4:5], 12, v[4:5]
	s_waitcnt lgkmcnt(6)
	v_cvt_pk_bf16_f32 v0, v6, v8
	s_waitcnt lgkmcnt(4)
	v_cvt_pk_bf16_f32 v1, v10, v12
	s_waitcnt lgkmcnt(2)
	v_cvt_pk_bf16_f32 v2, v14, v16
	s_waitcnt lgkmcnt(0)
	v_cvt_pk_bf16_f32 v3, v18, v22
	v_lshl_add_u64 v[4:5], v[20:21], 0, v[4:5]
	global_store_dwordx4 v[4:5], v[0:3], off
	v_or_b32_e32 v4, s14, v140
	v_ashrrev_i32_e32 v5, 31, v4
	v_lshlrev_b64 v[4:5], 12, v[4:5]
	v_cvt_pk_bf16_f32 v0, v7, v9
	v_cvt_pk_bf16_f32 v1, v11, v13
	v_cvt_pk_bf16_f32 v2, v15, v17
	v_cvt_pk_bf16_f32 v3, v19, v23
	v_lshl_add_u64 v[4:5], v[20:21], 0, v[4:5]
	global_store_dwordx4 v[4:5], v[0:3], off
	s_waitcnt lgkmcnt(0)
	s_add_i32 s14, s37, s39
	s_waitcnt vmcnt(8)
	v_mov_b64_e32 v[16:17], v[124:125]
	v_mov_b64_e32 v[0:1], v[120:121]
	v_mov_b64_e32 v[4:5], v[116:117]
	v_mov_b64_e32 v[8:9], v[112:113]
	v_mov_b64_e32 v[12:13], v[108:109]
	v_mov_b64_e32 v[20:21], v[104:105]
	v_mov_b64_e32 v[24:25], v[100:101]
	v_mov_b64_e32 v[28:29], v[96:97]
	v_mov_b64_e32 v[32:33], v[92:93]
	v_mov_b64_e32 v[36:37], v[88:89]
	v_mov_b64_e32 v[40:41], v[84:85]
	v_mov_b64_e32 v[44:45], v[80:81]
	v_mov_b64_e32 v[48:49], v[76:77]
	v_mov_b64_e32 v[52:53], v[72:73]
	v_mov_b64_e32 v[56:57], v[68:69]
	v_mov_b64_e32 v[60:61], v[64:65]
	s_cmpk_lt_i32 s14, 0x2800
	v_mov_b64_e32 v[18:19], v[126:127]
	v_mov_b64_e32 v[2:3], v[122:123]
	v_mov_b64_e32 v[6:7], v[118:119]
	v_mov_b64_e32 v[10:11], v[114:115]
	v_mov_b64_e32 v[14:15], v[110:111]
	v_mov_b64_e32 v[22:23], v[106:107]
	v_mov_b64_e32 v[26:27], v[102:103]
	v_mov_b64_e32 v[30:31], v[98:99]
	v_mov_b64_e32 v[34:35], v[94:95]
	v_mov_b64_e32 v[38:39], v[90:91]
	v_mov_b64_e32 v[42:43], v[86:87]
	v_mov_b64_e32 v[46:47], v[82:83]
	v_mov_b64_e32 v[50:51], v[78:79]
	v_mov_b64_e32 v[54:55], v[74:75]
	v_mov_b64_e32 v[58:59], v[70:71]
	v_mov_b64_e32 v[62:63], v[66:67]
	s_mov_b32 s36, s40
	s_mov_b64 s[18:19], s[20:21]
	s_mov_b32 s42, s41
	s_cbranch_scc0 .LBB0_594

.LBB0_934:
	v_cvt_pk_bf16_f32 v104, v112, v113
	v_cvt_pk_bf16_f32 v105, v114, v115
	v_cvt_pk_bf16_f32 v106, v116, v117
	v_cvt_pk_bf16_f32 v107, v118, v119
	v_lshl_add_u64 v[108:109], v[122:123], 0, v[144:145]
	s_and_b64 vcc, exec, s[4:5]
	s_mov_b64 s[24:25], -1
	global_store_dwordx4 v[108:109], v[104:107], off
	s_cbranch_vccnz .LBB0_936
	s_nop 0
	v_mul_f32_e32 v104, 0xbfb8aa3b, v100
	v_exp_f32_e32 v104, v104
	v_mul_f32_e32 v105, 0xbfb8aa3b, v96
	v_exp_f32_e32 v105, v105
	v_mul_f32_e32 v106, 0xbfb8aa3b, v101
	v_exp_f32_e32 v106, v106
	v_add_f32_e32 v104, 1.0, v104
	v_rcp_f32_e32 v104, v104
	v_add_f32_e32 v105, 1.0, v105
	v_rcp_f32_e32 v105, v105
	v_mul_f32_e32 v108, 0xbfb8aa3b, v97
	v_exp_f32_e32 v109, v108
	v_add_f32_e32 v106, 1.0, v106
	v_rcp_f32_e32 v106, v106
	v_mul_f32_e32 v107, v100, v104
	v_cndmask_b32_e64 v104, v104, v107, s[22:23]
	v_mul_f32_e32 v107, v96, v105
	v_cndmask_b32_e64 v108, v105, v107, s[22:23]
	v_add_f32_e32 v105, 1.0, v109
	v_rcp_f32_e32 v107, v105
	v_mul_f32_e32 v105, v101, v106
	v_cndmask_b32_e64 v105, v106, v105, s[22:23]
	v_mul_f32_e32 v106, 0xbfb8aa3b, v102
	v_exp_f32_e32 v106, v106
	v_mul_f32_e32 v110, 0xbfb8aa3b, v98
	v_exp_f32_e32 v110, v110
	v_mul_f32_e32 v109, v97, v107
	v_add_f32_e32 v106, 1.0, v106
	v_rcp_f32_e32 v106, v106
	v_cndmask_b32_e64 v109, v107, v109, s[22:23]
	v_add_f32_e32 v107, 1.0, v110
	v_mul_f32_e32 v111, 0xbfb8aa3b, v99
	v_mul_f32_e32 v110, v102, v106
	v_cndmask_b32_e64 v106, v106, v110, s[22:23]
	v_mul_f32_e32 v110, 0xbfb8aa3b, v103
	v_exp_f32_e32 v110, v110
	v_exp_f32_e32 v111, v111
	v_rcp_f32_e32 v107, v107
	s_mov_b64 s[24:25], 0
	v_add_f32_e32 v110, 1.0, v110
	v_rcp_f32_e32 v113, v110
	v_add_f32_e32 v110, 1.0, v111
	v_rcp_f32_e32 v111, v110
	v_mul_f32_e32 v112, v98, v107
	v_cndmask_b32_e64 v110, v107, v112, s[22:23]
	v_mul_f32_e32 v107, v103, v113
	v_mul_f32_e32 v112, v99, v111
	v_cndmask_b32_e64 v107, v113, v107, s[22:23]
	v_cndmask_b32_e64 v111, v111, v112, s[22:23]

.LBB0_938:
	v_mov_b32_e32 v121, v145
	s_lshl_b64 s[24:25], s[26:27], 4
	v_cvt_pk_bf16_f32 v96, v104, v105
	v_cvt_pk_bf16_f32 v97, v106, v107
	v_cvt_pk_bf16_f32 v98, v108, v109
	v_cvt_pk_bf16_f32 v99, v110, v111
	v_lshl_add_u64 v[100:101], v[122:123], 0, v[120:121]
	global_store_dwordx4 v[100:101], v[96:99], off
	v_lshl_add_u64 v[104:105], s[24:25], 1, v[122:123]
	s_and_b64 vcc, exec, s[4:5]
	s_mov_b64 s[28:29], -1
	s_cbranch_vccnz .LBB0_940
	v_mul_f32_e32 v96, 0xbfb8aa3b, v92
	v_exp_f32_e32 v96, v96
	v_mul_f32_e32 v97, 0xbfb8aa3b, v88
	v_exp_f32_e32 v97, v97
	v_mul_f32_e32 v98, 0xbfb8aa3b, v93
	v_exp_f32_e32 v98, v98
	v_add_f32_e32 v96, 1.0, v96
	v_rcp_f32_e32 v96, v96
	v_add_f32_e32 v97, 1.0, v97
	v_rcp_f32_e32 v97, v97
	v_mul_f32_e32 v100, 0xbfb8aa3b, v89
	v_exp_f32_e32 v101, v100
	v_add_f32_e32 v98, 1.0, v98
	v_rcp_f32_e32 v98, v98
	v_mul_f32_e32 v99, v92, v96
	v_cndmask_b32_e64 v96, v96, v99, s[22:23]
	v_mul_f32_e32 v99, v88, v97
	v_cndmask_b32_e64 v100, v97, v99, s[22:23]
	v_add_f32_e32 v97, 1.0, v101
	v_rcp_f32_e32 v99, v97
	v_mul_f32_e32 v97, v93, v98
	v_cndmask_b32_e64 v97, v98, v97, s[22:23]
	v_mul_f32_e32 v98, 0xbfb8aa3b, v94
	v_exp_f32_e32 v98, v98
	v_mul_f32_e32 v102, 0xbfb8aa3b, v90
	v_exp_f32_e32 v102, v102
	v_mul_f32_e32 v101, v89, v99
	v_add_f32_e32 v98, 1.0, v98
	v_rcp_f32_e32 v98, v98
	v_cndmask_b32_e64 v101, v99, v101, s[22:23]
	v_add_f32_e32 v99, 1.0, v102
	v_mul_f32_e32 v103, 0xbfb8aa3b, v91
	v_mul_f32_e32 v102, v94, v98
	v_cndmask_b32_e64 v98, v98, v102, s[22:23]
	v_mul_f32_e32 v102, 0xbfb8aa3b, v95
	v_exp_f32_e32 v102, v102
	v_exp_f32_e32 v103, v103
	v_rcp_f32_e32 v99, v99
	s_mov_b64 s[28:29], 0
	v_add_f32_e32 v102, 1.0, v102
	v_rcp_f32_e32 v107, v102
	v_add_f32_e32 v102, 1.0, v103
	v_rcp_f32_e32 v103, v102
	v_mul_f32_e32 v106, v90, v99
	v_cndmask_b32_e64 v102, v99, v106, s[22:23]
	v_mul_f32_e32 v99, v95, v107
	v_mul_f32_e32 v106, v91, v103
	v_cndmask_b32_e64 v99, v107, v99, s[22:23]
	v_cndmask_b32_e64 v103, v103, v106, s[22:23]

.LBB0_942:
	v_cvt_pk_bf16_f32 v88, v96, v97
	v_cvt_pk_bf16_f32 v89, v98, v99
	v_cvt_pk_bf16_f32 v90, v100, v101
	v_cvt_pk_bf16_f32 v91, v102, v103
	v_lshl_add_u64 v[92:93], v[104:105], 0, v[144:145]
	s_and_b64 vcc, exec, s[4:5]
	s_mov_b64 s[28:29], -1
	global_store_dwordx4 v[92:93], v[88:91], off
	s_cbranch_vccnz .LBB0_944
	s_nop 0
	v_mul_f32_e32 v88, 0xbfb8aa3b, v84
	v_exp_f32_e32 v88, v88
	v_mul_f32_e32 v89, 0xbfb8aa3b, v80
	v_exp_f32_e32 v89, v89
	v_mul_f32_e32 v90, 0xbfb8aa3b, v85
	v_exp_f32_e32 v90, v90
	v_add_f32_e32 v88, 1.0, v88
	v_rcp_f32_e32 v88, v88
	v_add_f32_e32 v89, 1.0, v89
	v_rcp_f32_e32 v89, v89
	v_mul_f32_e32 v92, 0xbfb8aa3b, v81
	v_exp_f32_e32 v93, v92
	v_add_f32_e32 v90, 1.0, v90
	v_rcp_f32_e32 v90, v90
	v_mul_f32_e32 v91, v84, v88
	v_cndmask_b32_e64 v88, v88, v91, s[22:23]
	v_mul_f32_e32 v91, v80, v89
	v_cndmask_b32_e64 v92, v89, v91, s[22:23]
	v_add_f32_e32 v89, 1.0, v93
	v_rcp_f32_e32 v91, v89
	v_mul_f32_e32 v89, v85, v90
	v_cndmask_b32_e64 v89, v90, v89, s[22:23]
	v_mul_f32_e32 v90, 0xbfb8aa3b, v86
	v_exp_f32_e32 v90, v90
	v_mul_f32_e32 v94, 0xbfb8aa3b, v82
	v_exp_f32_e32 v94, v94
	v_mul_f32_e32 v93, v81, v91
	v_add_f32_e32 v90, 1.0, v90
	v_rcp_f32_e32 v90, v90
	v_cndmask_b32_e64 v93, v91, v93, s[22:23]
	v_add_f32_e32 v91, 1.0, v94
	v_mul_f32_e32 v95, 0xbfb8aa3b, v83
	v_mul_f32_e32 v94, v86, v90
	v_cndmask_b32_e64 v90, v90, v94, s[22:23]
	v_mul_f32_e32 v94, 0xbfb8aa3b, v87
	v_exp_f32_e32 v94, v94
	v_exp_f32_e32 v95, v95
	v_rcp_f32_e32 v91, v91
	s_mov_b64 s[28:29], 0
	v_add_f32_e32 v94, 1.0, v94
	v_rcp_f32_e32 v97, v94
	v_add_f32_e32 v94, 1.0, v95
	v_rcp_f32_e32 v95, v94
	v_mul_f32_e32 v96, v82, v91
	v_cndmask_b32_e64 v94, v91, v96, s[22:23]
	v_mul_f32_e32 v91, v87, v97
	v_mul_f32_e32 v96, v83, v95
	v_cndmask_b32_e64 v91, v97, v91, s[22:23]
	v_cndmask_b32_e64 v95, v95, v96, s[22:23]

.LBB0_946:
	v_mov_b32_e32 v121, v145
	v_cvt_pk_bf16_f32 v80, v88, v89
	v_cvt_pk_bf16_f32 v81, v90, v91
	v_cvt_pk_bf16_f32 v82, v92, v93
	v_cvt_pk_bf16_f32 v83, v94, v95
	v_lshl_add_u64 v[84:85], v[104:105], 0, v[120:121]
	global_store_dwordx4 v[84:85], v[80:83], off
	v_lshl_add_u64 v[88:89], s[24:25], 1, v[104:105]
	s_and_b64 vcc, exec, s[4:5]
	s_mov_b64 s[28:29], -1
	s_cbranch_vccnz .LBB0_948
	v_mul_f32_e32 v80, 0xbfb8aa3b, v76
	v_exp_f32_e32 v80, v80
	v_mul_f32_e32 v81, 0xbfb8aa3b, v72
	v_exp_f32_e32 v81, v81
	v_mul_f32_e32 v82, 0xbfb8aa3b, v77
	v_exp_f32_e32 v82, v82
	v_add_f32_e32 v80, 1.0, v80
	v_rcp_f32_e32 v80, v80
	v_add_f32_e32 v81, 1.0, v81
	v_rcp_f32_e32 v81, v81
	v_mul_f32_e32 v84, 0xbfb8aa3b, v73
	v_exp_f32_e32 v85, v84
	v_add_f32_e32 v82, 1.0, v82
	v_rcp_f32_e32 v82, v82
	v_mul_f32_e32 v83, v76, v80
	v_cndmask_b32_e64 v80, v80, v83, s[22:23]
	v_mul_f32_e32 v83, v72, v81
	v_cndmask_b32_e64 v84, v81, v83, s[22:23]
	v_add_f32_e32 v81, 1.0, v85
	v_rcp_f32_e32 v83, v81
	v_mul_f32_e32 v81, v77, v82
	v_cndmask_b32_e64 v81, v82, v81, s[22:23]
	v_mul_f32_e32 v82, 0xbfb8aa3b, v78
	v_exp_f32_e32 v82, v82
	v_mul_f32_e32 v86, 0xbfb8aa3b, v74
	v_exp_f32_e32 v86, v86
	v_mul_f32_e32 v85, v73, v83
	v_add_f32_e32 v82, 1.0, v82
	v_rcp_f32_e32 v82, v82
	v_cndmask_b32_e64 v85, v83, v85, s[22:23]
	v_add_f32_e32 v83, 1.0, v86
	v_mul_f32_e32 v87, 0xbfb8aa3b, v75
	v_mul_f32_e32 v86, v78, v82
	v_cndmask_b32_e64 v82, v82, v86, s[22:23]
	v_mul_f32_e32 v86, 0xbfb8aa3b, v79
	v_exp_f32_e32 v86, v86
	v_exp_f32_e32 v87, v87
	v_rcp_f32_e32 v83, v83
	s_mov_b64 s[28:29], 0
	v_add_f32_e32 v86, 1.0, v86
	v_rcp_f32_e32 v91, v86
	v_add_f32_e32 v86, 1.0, v87
	v_rcp_f32_e32 v87, v86
	v_mul_f32_e32 v90, v74, v83
	v_cndmask_b32_e64 v86, v83, v90, s[22:23]
	v_mul_f32_e32 v83, v79, v91
	v_mul_f32_e32 v90, v75, v87
	v_cndmask_b32_e64 v83, v91, v83, s[22:23]
	v_cndmask_b32_e64 v87, v87, v90, s[22:23]

.LBB0_950:
	v_cvt_pk_bf16_f32 v72, v80, v81
	v_cvt_pk_bf16_f32 v73, v82, v83
	v_cvt_pk_bf16_f32 v74, v84, v85
	v_cvt_pk_bf16_f32 v75, v86, v87
	v_lshl_add_u64 v[76:77], v[88:89], 0, v[144:145]
	s_and_b64 vcc, exec, s[4:5]
	s_mov_b64 s[28:29], -1
	global_store_dwordx4 v[76:77], v[72:75], off
	s_cbranch_vccnz .LBB0_952
	s_nop 0
	v_mul_f32_e32 v72, 0xbfb8aa3b, v68
	v_exp_f32_e32 v72, v72
	v_mul_f32_e32 v73, 0xbfb8aa3b, v64
	v_exp_f32_e32 v73, v73
	v_mul_f32_e32 v74, 0xbfb8aa3b, v69
	v_exp_f32_e32 v74, v74
	v_add_f32_e32 v72, 1.0, v72
	v_rcp_f32_e32 v72, v72
	v_add_f32_e32 v73, 1.0, v73
	v_rcp_f32_e32 v73, v73
	v_mul_f32_e32 v76, 0xbfb8aa3b, v65
	v_exp_f32_e32 v77, v76
	v_add_f32_e32 v74, 1.0, v74
	v_rcp_f32_e32 v74, v74
	v_mul_f32_e32 v75, v68, v72
	v_cndmask_b32_e64 v72, v72, v75, s[22:23]
	v_mul_f32_e32 v75, v64, v73
	v_cndmask_b32_e64 v76, v73, v75, s[22:23]
	v_add_f32_e32 v73, 1.0, v77
	v_rcp_f32_e32 v75, v73
	v_mul_f32_e32 v73, v69, v74
	v_cndmask_b32_e64 v73, v74, v73, s[22:23]
	v_mul_f32_e32 v74, 0xbfb8aa3b, v70
	v_exp_f32_e32 v74, v74
	v_mul_f32_e32 v78, 0xbfb8aa3b, v66
	v_exp_f32_e32 v78, v78
	v_mul_f32_e32 v77, v65, v75
	v_add_f32_e32 v74, 1.0, v74
	v_rcp_f32_e32 v74, v74
	v_cndmask_b32_e64 v77, v75, v77, s[22:23]
	v_add_f32_e32 v75, 1.0, v78
	v_mul_f32_e32 v79, 0xbfb8aa3b, v67
	v_mul_f32_e32 v78, v70, v74
	v_cndmask_b32_e64 v74, v74, v78, s[22:23]
	v_mul_f32_e32 v78, 0xbfb8aa3b, v71
	v_exp_f32_e32 v78, v78
	v_exp_f32_e32 v79, v79
	v_rcp_f32_e32 v75, v75
	s_mov_b64 s[28:29], 0
	v_add_f32_e32 v78, 1.0, v78
	v_rcp_f32_e32 v81, v78
	v_add_f32_e32 v78, 1.0, v79
	v_rcp_f32_e32 v79, v78
	v_mul_f32_e32 v80, v66, v75
	v_cndmask_b32_e64 v78, v75, v80, s[22:23]
	v_mul_f32_e32 v75, v71, v81
	v_mul_f32_e32 v80, v67, v79
	v_cndmask_b32_e64 v75, v81, v75, s[22:23]
	v_cndmask_b32_e64 v79, v79, v80, s[22:23]

.LBB0_954:
	v_mov_b32_e32 v121, v145
	v_cvt_pk_bf16_f32 v64, v72, v73
	v_cvt_pk_bf16_f32 v65, v74, v75
	v_cvt_pk_bf16_f32 v66, v76, v77
	v_cvt_pk_bf16_f32 v67, v78, v79
	v_lshl_add_u64 v[68:69], v[88:89], 0, v[120:121]
	s_mul_i32 s0, s26, 0x50
	global_store_dwordx4 v[68:69], v[64:67], off
	v_lshl_add_u64 v[72:73], s[0:1], 1, v[88:89]
	s_and_b64 vcc, exec, s[4:5]
	s_mov_b64 s[26:27], -1
	s_cbranch_vccnz .LBB0_956
	v_mul_f32_e32 v64, 0xbfb8aa3b, v60
	v_exp_f32_e32 v64, v64
	v_mul_f32_e32 v65, 0xbfb8aa3b, v56
	v_exp_f32_e32 v65, v65
	v_mul_f32_e32 v66, 0xbfb8aa3b, v61
	v_exp_f32_e32 v66, v66
	v_add_f32_e32 v64, 1.0, v64
	v_rcp_f32_e32 v64, v64
	v_add_f32_e32 v65, 1.0, v65
	v_rcp_f32_e32 v65, v65
	v_mul_f32_e32 v68, 0xbfb8aa3b, v57
	v_exp_f32_e32 v69, v68
	v_add_f32_e32 v66, 1.0, v66
	v_rcp_f32_e32 v66, v66
	v_mul_f32_e32 v67, v60, v64
	v_cndmask_b32_e64 v64, v64, v67, s[22:23]
	v_mul_f32_e32 v67, v56, v65
	v_cndmask_b32_e64 v68, v65, v67, s[22:23]
	v_add_f32_e32 v65, 1.0, v69
	v_rcp_f32_e32 v67, v65
	v_mul_f32_e32 v65, v61, v66
	v_cndmask_b32_e64 v65, v66, v65, s[22:23]
	v_mul_f32_e32 v66, 0xbfb8aa3b, v62
	v_exp_f32_e32 v66, v66
	v_mul_f32_e32 v70, 0xbfb8aa3b, v58
	v_exp_f32_e32 v70, v70
	v_mul_f32_e32 v69, v57, v67
	v_add_f32_e32 v66, 1.0, v66
	v_rcp_f32_e32 v66, v66
	v_cndmask_b32_e64 v69, v67, v69, s[22:23]
	v_add_f32_e32 v67, 1.0, v70
	v_mul_f32_e32 v71, 0xbfb8aa3b, v59
	v_mul_f32_e32 v70, v62, v66
	v_cndmask_b32_e64 v66, v66, v70, s[22:23]
	v_mul_f32_e32 v70, 0xbfb8aa3b, v63
	v_exp_f32_e32 v70, v70
	v_exp_f32_e32 v71, v71
	v_rcp_f32_e32 v67, v67
	s_mov_b64 s[26:27], 0
	v_add_f32_e32 v70, 1.0, v70
	v_rcp_f32_e32 v75, v70
	v_add_f32_e32 v70, 1.0, v71
	v_rcp_f32_e32 v71, v70
	v_mul_f32_e32 v74, v58, v67
	v_cndmask_b32_e64 v70, v67, v74, s[22:23]
	v_mul_f32_e32 v67, v63, v75
	v_mul_f32_e32 v74, v59, v71
	v_cndmask_b32_e64 v67, v75, v67, s[22:23]
	v_cndmask_b32_e64 v71, v71, v74, s[22:23]

.LBB0_958:
	v_cvt_pk_bf16_f32 v56, v64, v65
	v_cvt_pk_bf16_f32 v57, v66, v67
	v_cvt_pk_bf16_f32 v58, v68, v69
	v_cvt_pk_bf16_f32 v59, v70, v71
	v_lshl_add_u64 v[60:61], v[72:73], 0, v[144:145]
	s_and_b64 vcc, exec, s[4:5]
	s_mov_b64 s[26:27], -1
	global_store_dwordx4 v[60:61], v[56:59], off
	s_cbranch_vccnz .LBB0_960
	s_nop 0
	v_mul_f32_e32 v56, 0xbfb8aa3b, v52
	v_exp_f32_e32 v56, v56
	v_mul_f32_e32 v57, 0xbfb8aa3b, v48
	v_exp_f32_e32 v57, v57
	v_mul_f32_e32 v58, 0xbfb8aa3b, v53
	v_exp_f32_e32 v58, v58
	v_add_f32_e32 v56, 1.0, v56
	v_rcp_f32_e32 v56, v56
	v_add_f32_e32 v57, 1.0, v57
	v_rcp_f32_e32 v57, v57
	v_mul_f32_e32 v60, 0xbfb8aa3b, v49
	v_exp_f32_e32 v61, v60
	v_add_f32_e32 v58, 1.0, v58
	v_rcp_f32_e32 v58, v58
	v_mul_f32_e32 v59, v52, v56
	v_cndmask_b32_e64 v56, v56, v59, s[22:23]
	v_mul_f32_e32 v59, v48, v57
	v_cndmask_b32_e64 v60, v57, v59, s[22:23]
	v_add_f32_e32 v57, 1.0, v61
	v_rcp_f32_e32 v59, v57
	v_mul_f32_e32 v57, v53, v58
	v_cndmask_b32_e64 v57, v58, v57, s[22:23]
	v_mul_f32_e32 v58, 0xbfb8aa3b, v54
	v_exp_f32_e32 v58, v58
	v_mul_f32_e32 v62, 0xbfb8aa3b, v50
	v_exp_f32_e32 v62, v62
	v_mul_f32_e32 v61, v49, v59
	v_add_f32_e32 v58, 1.0, v58
	v_rcp_f32_e32 v58, v58
	v_cndmask_b32_e64 v61, v59, v61, s[22:23]
	v_add_f32_e32 v59, 1.0, v62
	v_mul_f32_e32 v63, 0xbfb8aa3b, v51
	v_mul_f32_e32 v62, v54, v58
	v_cndmask_b32_e64 v58, v58, v62, s[22:23]
	v_mul_f32_e32 v62, 0xbfb8aa3b, v55
	v_exp_f32_e32 v62, v62
	v_exp_f32_e32 v63, v63
	v_rcp_f32_e32 v59, v59
	s_mov_b64 s[26:27], 0
	v_add_f32_e32 v62, 1.0, v62
	v_rcp_f32_e32 v65, v62
	v_add_f32_e32 v62, 1.0, v63
	v_rcp_f32_e32 v63, v62
	v_mul_f32_e32 v64, v50, v59
	v_cndmask_b32_e64 v62, v59, v64, s[22:23]
	v_mul_f32_e32 v59, v55, v65
	v_mul_f32_e32 v64, v51, v63
	v_cndmask_b32_e64 v59, v65, v59, s[22:23]
	v_cndmask_b32_e64 v63, v63, v64, s[22:23]

.LBB0_962:
	v_mov_b32_e32 v121, v145
	v_cvt_pk_bf16_f32 v48, v56, v57
	v_cvt_pk_bf16_f32 v49, v58, v59
	v_cvt_pk_bf16_f32 v50, v60, v61
	v_cvt_pk_bf16_f32 v51, v62, v63
	v_lshl_add_u64 v[52:53], v[72:73], 0, v[120:121]
	global_store_dwordx4 v[52:53], v[48:51], off
	v_lshl_add_u64 v[56:57], s[24:25], 1, v[72:73]
	s_and_b64 vcc, exec, s[4:5]
	s_mov_b64 s[26:27], -1
	s_cbranch_vccnz .LBB0_964
	v_mul_f32_e32 v48, 0xbfb8aa3b, v44
	v_exp_f32_e32 v48, v48
	v_mul_f32_e32 v49, 0xbfb8aa3b, v40
	v_exp_f32_e32 v49, v49
	v_mul_f32_e32 v50, 0xbfb8aa3b, v45
	v_exp_f32_e32 v50, v50
	v_add_f32_e32 v48, 1.0, v48
	v_rcp_f32_e32 v48, v48
	v_add_f32_e32 v49, 1.0, v49
	v_rcp_f32_e32 v49, v49
	v_mul_f32_e32 v52, 0xbfb8aa3b, v41
	v_exp_f32_e32 v53, v52
	v_add_f32_e32 v50, 1.0, v50
	v_rcp_f32_e32 v50, v50
	v_mul_f32_e32 v51, v44, v48
	v_cndmask_b32_e64 v48, v48, v51, s[22:23]
	v_mul_f32_e32 v51, v40, v49
	v_cndmask_b32_e64 v52, v49, v51, s[22:23]
	v_add_f32_e32 v49, 1.0, v53
	v_rcp_f32_e32 v51, v49
	v_mul_f32_e32 v49, v45, v50
	v_cndmask_b32_e64 v49, v50, v49, s[22:23]
	v_mul_f32_e32 v50, 0xbfb8aa3b, v46
	v_exp_f32_e32 v50, v50
	v_mul_f32_e32 v54, 0xbfb8aa3b, v42
	v_exp_f32_e32 v54, v54
	v_mul_f32_e32 v53, v41, v51
	v_add_f32_e32 v50, 1.0, v50
	v_rcp_f32_e32 v50, v50
	v_cndmask_b32_e64 v53, v51, v53, s[22:23]
	v_add_f32_e32 v51, 1.0, v54
	v_mul_f32_e32 v55, 0xbfb8aa3b, v43
	v_mul_f32_e32 v54, v46, v50
	v_cndmask_b32_e64 v50, v50, v54, s[22:23]
	v_mul_f32_e32 v54, 0xbfb8aa3b, v47
	v_exp_f32_e32 v54, v54
	v_exp_f32_e32 v55, v55
	v_rcp_f32_e32 v51, v51
	s_mov_b64 s[26:27], 0
	v_add_f32_e32 v54, 1.0, v54
	v_rcp_f32_e32 v59, v54
	v_add_f32_e32 v54, 1.0, v55
	v_rcp_f32_e32 v55, v54
	v_mul_f32_e32 v58, v42, v51
	v_cndmask_b32_e64 v54, v51, v58, s[22:23]
	v_mul_f32_e32 v51, v47, v59
	v_mul_f32_e32 v58, v43, v55
	v_cndmask_b32_e64 v51, v59, v51, s[22:23]
	v_cndmask_b32_e64 v55, v55, v58, s[22:23]

.LBB0_966:
	v_cvt_pk_bf16_f32 v40, v48, v49
	v_cvt_pk_bf16_f32 v41, v50, v51
	v_cvt_pk_bf16_f32 v42, v52, v53
	v_cvt_pk_bf16_f32 v43, v54, v55
	v_lshl_add_u64 v[44:45], v[56:57], 0, v[144:145]
	s_and_b64 vcc, exec, s[4:5]
	s_mov_b64 s[26:27], -1
	global_store_dwordx4 v[44:45], v[40:43], off
	s_cbranch_vccnz .LBB0_968
	s_nop 0
	v_mul_f32_e32 v40, 0xbfb8aa3b, v36
	v_exp_f32_e32 v40, v40
	v_mul_f32_e32 v41, 0xbfb8aa3b, v32
	v_exp_f32_e32 v41, v41
	v_mul_f32_e32 v42, 0xbfb8aa3b, v37
	v_exp_f32_e32 v42, v42
	v_add_f32_e32 v40, 1.0, v40
	v_rcp_f32_e32 v40, v40
	v_add_f32_e32 v41, 1.0, v41
	v_rcp_f32_e32 v41, v41
	v_mul_f32_e32 v44, 0xbfb8aa3b, v33
	v_exp_f32_e32 v45, v44
	v_add_f32_e32 v42, 1.0, v42
	v_rcp_f32_e32 v42, v42
	v_mul_f32_e32 v43, v36, v40
	v_cndmask_b32_e64 v40, v40, v43, s[22:23]
	v_mul_f32_e32 v43, v32, v41
	v_cndmask_b32_e64 v44, v41, v43, s[22:23]
	v_add_f32_e32 v41, 1.0, v45
	v_rcp_f32_e32 v43, v41
	v_mul_f32_e32 v41, v37, v42
	v_cndmask_b32_e64 v41, v42, v41, s[22:23]
	v_mul_f32_e32 v42, 0xbfb8aa3b, v38
	v_exp_f32_e32 v42, v42
	v_mul_f32_e32 v46, 0xbfb8aa3b, v34
	v_exp_f32_e32 v46, v46
	v_mul_f32_e32 v45, v33, v43
	v_add_f32_e32 v42, 1.0, v42
	v_rcp_f32_e32 v42, v42
	v_cndmask_b32_e64 v45, v43, v45, s[22:23]
	v_add_f32_e32 v43, 1.0, v46
	v_mul_f32_e32 v47, 0xbfb8aa3b, v35
	v_mul_f32_e32 v46, v38, v42
	v_cndmask_b32_e64 v42, v42, v46, s[22:23]
	v_mul_f32_e32 v46, 0xbfb8aa3b, v39
	v_exp_f32_e32 v46, v46
	v_exp_f32_e32 v47, v47
	v_rcp_f32_e32 v43, v43
	s_mov_b64 s[26:27], 0
	v_add_f32_e32 v46, 1.0, v46
	v_rcp_f32_e32 v49, v46
	v_add_f32_e32 v46, 1.0, v47
	v_rcp_f32_e32 v47, v46
	v_mul_f32_e32 v48, v34, v43
	v_cndmask_b32_e64 v46, v43, v48, s[22:23]
	v_mul_f32_e32 v43, v39, v49
	v_mul_f32_e32 v48, v35, v47
	v_cndmask_b32_e64 v43, v49, v43, s[22:23]
	v_cndmask_b32_e64 v47, v47, v48, s[22:23]

.LBB0_970:
	v_mov_b32_e32 v121, v145
	v_cvt_pk_bf16_f32 v32, v40, v41
	v_cvt_pk_bf16_f32 v33, v42, v43
	v_cvt_pk_bf16_f32 v34, v44, v45
	v_cvt_pk_bf16_f32 v35, v46, v47
	v_lshl_add_u64 v[36:37], v[56:57], 0, v[120:121]
	global_store_dwordx4 v[36:37], v[32:35], off
	v_lshl_add_u64 v[40:41], s[24:25], 1, v[56:57]
	s_and_b64 vcc, exec, s[4:5]
	s_mov_b64 s[26:27], -1
	s_cbranch_vccnz .LBB0_972
	v_mul_f32_e32 v32, 0xbfb8aa3b, v28
	v_exp_f32_e32 v32, v32
	v_mul_f32_e32 v33, 0xbfb8aa3b, v24
	v_exp_f32_e32 v33, v33
	v_mul_f32_e32 v34, 0xbfb8aa3b, v29
	v_exp_f32_e32 v34, v34
	v_add_f32_e32 v32, 1.0, v32
	v_rcp_f32_e32 v32, v32
	v_add_f32_e32 v33, 1.0, v33
	v_rcp_f32_e32 v33, v33
	v_mul_f32_e32 v36, 0xbfb8aa3b, v25
	v_exp_f32_e32 v37, v36
	v_add_f32_e32 v34, 1.0, v34
	v_rcp_f32_e32 v34, v34
	v_mul_f32_e32 v35, v28, v32
	v_cndmask_b32_e64 v32, v32, v35, s[22:23]
	v_mul_f32_e32 v35, v24, v33
	v_cndmask_b32_e64 v36, v33, v35, s[22:23]
	v_add_f32_e32 v33, 1.0, v37
	v_rcp_f32_e32 v35, v33
	v_mul_f32_e32 v33, v29, v34
	v_cndmask_b32_e64 v33, v34, v33, s[22:23]
	v_mul_f32_e32 v34, 0xbfb8aa3b, v30
	v_exp_f32_e32 v34, v34
	v_mul_f32_e32 v38, 0xbfb8aa3b, v26
	v_exp_f32_e32 v38, v38
	v_mul_f32_e32 v37, v25, v35
	v_add_f32_e32 v34, 1.0, v34
	v_rcp_f32_e32 v34, v34
	v_cndmask_b32_e64 v37, v35, v37, s[22:23]
	v_add_f32_e32 v35, 1.0, v38
	v_mul_f32_e32 v39, 0xbfb8aa3b, v27
	v_mul_f32_e32 v38, v30, v34
	v_cndmask_b32_e64 v34, v34, v38, s[22:23]
	v_mul_f32_e32 v38, 0xbfb8aa3b, v31
	v_exp_f32_e32 v38, v38
	v_exp_f32_e32 v39, v39
	v_rcp_f32_e32 v35, v35
	s_mov_b64 s[26:27], 0
	v_add_f32_e32 v38, 1.0, v38
	v_rcp_f32_e32 v43, v38
	v_add_f32_e32 v38, 1.0, v39
	v_rcp_f32_e32 v39, v38
	v_mul_f32_e32 v42, v26, v35
	v_cndmask_b32_e64 v38, v35, v42, s[22:23]
	v_mul_f32_e32 v35, v31, v43
	v_mul_f32_e32 v42, v27, v39
	v_cndmask_b32_e64 v35, v43, v35, s[22:23]
	v_cndmask_b32_e64 v39, v39, v42, s[22:23]

.LBB0_974:
	v_cvt_pk_bf16_f32 v24, v32, v33
	v_cvt_pk_bf16_f32 v25, v34, v35
	v_cvt_pk_bf16_f32 v26, v36, v37
	v_cvt_pk_bf16_f32 v27, v38, v39
	v_lshl_add_u64 v[28:29], v[40:41], 0, v[144:145]
	s_and_b64 vcc, exec, s[4:5]
	s_mov_b64 s[26:27], -1
	global_store_dwordx4 v[28:29], v[24:27], off
	s_cbranch_vccnz .LBB0_976
	s_nop 0
	v_mul_f32_e32 v24, 0xbfb8aa3b, v20
	v_exp_f32_e32 v24, v24
	v_mul_f32_e32 v25, 0xbfb8aa3b, v16
	v_exp_f32_e32 v25, v25
	v_mul_f32_e32 v26, 0xbfb8aa3b, v21
	v_exp_f32_e32 v26, v26
	v_add_f32_e32 v24, 1.0, v24
	v_rcp_f32_e32 v24, v24
	v_add_f32_e32 v25, 1.0, v25
	v_rcp_f32_e32 v25, v25
	v_mul_f32_e32 v28, 0xbfb8aa3b, v17
	v_exp_f32_e32 v29, v28
	v_add_f32_e32 v26, 1.0, v26
	v_rcp_f32_e32 v26, v26
	v_mul_f32_e32 v27, v20, v24
	v_cndmask_b32_e64 v24, v24, v27, s[22:23]
	v_mul_f32_e32 v27, v16, v25
	v_cndmask_b32_e64 v28, v25, v27, s[22:23]
	v_add_f32_e32 v25, 1.0, v29
	v_rcp_f32_e32 v27, v25
	v_mul_f32_e32 v25, v21, v26
	v_cndmask_b32_e64 v25, v26, v25, s[22:23]
	v_mul_f32_e32 v26, 0xbfb8aa3b, v22
	v_exp_f32_e32 v26, v26
	v_mul_f32_e32 v30, 0xbfb8aa3b, v18
	v_exp_f32_e32 v30, v30
	v_mul_f32_e32 v29, v17, v27
	v_add_f32_e32 v26, 1.0, v26
	v_rcp_f32_e32 v26, v26
	v_cndmask_b32_e64 v29, v27, v29, s[22:23]
	v_add_f32_e32 v27, 1.0, v30
	v_mul_f32_e32 v31, 0xbfb8aa3b, v19
	v_mul_f32_e32 v30, v22, v26
	v_cndmask_b32_e64 v26, v26, v30, s[22:23]
	v_mul_f32_e32 v30, 0xbfb8aa3b, v23
	v_exp_f32_e32 v30, v30
	v_exp_f32_e32 v31, v31
	v_rcp_f32_e32 v27, v27
	s_mov_b64 s[26:27], 0
	v_add_f32_e32 v30, 1.0, v30
	v_rcp_f32_e32 v33, v30
	v_add_f32_e32 v30, 1.0, v31
	v_rcp_f32_e32 v31, v30
	v_mul_f32_e32 v32, v18, v27
	v_cndmask_b32_e64 v30, v27, v32, s[22:23]
	v_mul_f32_e32 v27, v23, v33
	v_mul_f32_e32 v32, v19, v31
	v_cndmask_b32_e64 v27, v33, v27, s[22:23]
	v_cndmask_b32_e64 v31, v31, v32, s[22:23]

.LBB0_978:
	v_mov_b32_e32 v121, v145
	v_cvt_pk_bf16_f32 v16, v24, v25
	v_cvt_pk_bf16_f32 v17, v26, v27
	v_cvt_pk_bf16_f32 v18, v28, v29
	v_cvt_pk_bf16_f32 v19, v30, v31
	v_lshl_add_u64 v[20:21], v[40:41], 0, v[120:121]
	global_store_dwordx4 v[20:21], v[16:19], off
	v_lshl_add_u64 v[24:25], s[24:25], 1, v[40:41]
	s_and_b64 vcc, exec, s[4:5]
	s_mov_b64 s[24:25], -1
	s_cbranch_vccnz .LBB0_980
	v_mul_f32_e32 v16, 0xbfb8aa3b, v12
	v_exp_f32_e32 v16, v16
	v_mul_f32_e32 v17, 0xbfb8aa3b, v8
	v_exp_f32_e32 v17, v17
	v_mul_f32_e32 v18, 0xbfb8aa3b, v13
	v_exp_f32_e32 v18, v18
	v_add_f32_e32 v16, 1.0, v16
	v_rcp_f32_e32 v16, v16
	v_add_f32_e32 v17, 1.0, v17
	v_rcp_f32_e32 v17, v17
	v_mul_f32_e32 v20, 0xbfb8aa3b, v9
	v_exp_f32_e32 v21, v20
	v_add_f32_e32 v18, 1.0, v18
	v_rcp_f32_e32 v18, v18
	v_mul_f32_e32 v19, v12, v16
	v_cndmask_b32_e64 v16, v16, v19, s[22:23]
	v_mul_f32_e32 v19, v8, v17
	v_cndmask_b32_e64 v20, v17, v19, s[22:23]
	v_add_f32_e32 v17, 1.0, v21
	v_rcp_f32_e32 v19, v17
	v_mul_f32_e32 v17, v13, v18
	v_cndmask_b32_e64 v17, v18, v17, s[22:23]
	v_mul_f32_e32 v18, 0xbfb8aa3b, v14
	v_exp_f32_e32 v18, v18
	v_mul_f32_e32 v22, 0xbfb8aa3b, v10
	v_exp_f32_e32 v22, v22
	v_mul_f32_e32 v21, v9, v19
	v_add_f32_e32 v18, 1.0, v18
	v_rcp_f32_e32 v18, v18
	v_cndmask_b32_e64 v21, v19, v21, s[22:23]
	v_add_f32_e32 v19, 1.0, v22
	v_mul_f32_e32 v23, 0xbfb8aa3b, v11
	v_mul_f32_e32 v22, v14, v18
	v_cndmask_b32_e64 v18, v18, v22, s[22:23]
	v_mul_f32_e32 v22, 0xbfb8aa3b, v15
	v_exp_f32_e32 v22, v22
	v_exp_f32_e32 v23, v23
	v_rcp_f32_e32 v19, v19
	s_mov_b64 s[24:25], 0
	v_add_f32_e32 v22, 1.0, v22
	v_rcp_f32_e32 v27, v22
	v_add_f32_e32 v22, 1.0, v23
	v_rcp_f32_e32 v23, v22
	v_mul_f32_e32 v26, v10, v19
	v_cndmask_b32_e64 v22, v19, v26, s[22:23]
	v_mul_f32_e32 v19, v15, v27
	v_mul_f32_e32 v26, v11, v23
	v_cndmask_b32_e64 v19, v27, v19, s[22:23]
	v_cndmask_b32_e64 v23, v23, v26, s[22:23]

.LBB0_982:
	v_cvt_pk_bf16_f32 v8, v16, v17
	v_cvt_pk_bf16_f32 v9, v18, v19
	v_cvt_pk_bf16_f32 v10, v20, v21
	v_cvt_pk_bf16_f32 v11, v22, v23
	v_lshl_add_u64 v[12:13], v[24:25], 0, v[144:145]
	s_and_b64 vcc, exec, s[4:5]
	s_mov_b64 s[4:5], -1
	global_store_dwordx4 v[12:13], v[8:11], off
	s_cbranch_vccnz .LBB0_984
	s_nop 0
	v_mul_f32_e32 v8, 0xbfb8aa3b, v4
	v_exp_f32_e32 v8, v8
	v_mul_f32_e32 v9, 0xbfb8aa3b, v0
	v_exp_f32_e32 v9, v9
	v_mul_f32_e32 v10, 0xbfb8aa3b, v5
	v_exp_f32_e32 v10, v10
	v_add_f32_e32 v8, 1.0, v8
	v_rcp_f32_e32 v8, v8
	v_add_f32_e32 v9, 1.0, v9
	v_rcp_f32_e32 v9, v9
	v_mul_f32_e32 v12, 0xbfb8aa3b, v1
	v_exp_f32_e32 v13, v12
	v_add_f32_e32 v10, 1.0, v10
	v_rcp_f32_e32 v10, v10
	v_mul_f32_e32 v11, v4, v8
	v_cndmask_b32_e64 v8, v8, v11, s[22:23]
	v_mul_f32_e32 v11, v0, v9
	v_cndmask_b32_e64 v12, v9, v11, s[22:23]
	v_add_f32_e32 v9, 1.0, v13
	v_rcp_f32_e32 v11, v9
	v_mul_f32_e32 v9, v5, v10
	v_cndmask_b32_e64 v9, v10, v9, s[22:23]
	v_mul_f32_e32 v10, 0xbfb8aa3b, v6
	v_exp_f32_e32 v10, v10
	v_mul_f32_e32 v14, 0xbfb8aa3b, v2
	v_exp_f32_e32 v14, v14
	v_mul_f32_e32 v13, v1, v11
	v_add_f32_e32 v10, 1.0, v10
	v_rcp_f32_e32 v10, v10
	v_cndmask_b32_e64 v13, v11, v13, s[22:23]
	v_add_f32_e32 v11, 1.0, v14
	v_mul_f32_e32 v15, 0xbfb8aa3b, v3
	v_mul_f32_e32 v14, v6, v10
	v_cndmask_b32_e64 v10, v10, v14, s[22:23]
	v_mul_f32_e32 v14, 0xbfb8aa3b, v7
	v_exp_f32_e32 v14, v14
	v_exp_f32_e32 v15, v15
	v_rcp_f32_e32 v11, v11
	s_mov_b64 s[4:5], 0
	v_add_f32_e32 v14, 1.0, v14
	v_rcp_f32_e32 v17, v14
	v_add_f32_e32 v14, 1.0, v15
	v_rcp_f32_e32 v15, v14
	v_mul_f32_e32 v16, v2, v11
	v_cndmask_b32_e64 v14, v11, v16, s[22:23]
	v_mul_f32_e32 v11, v7, v17
	v_mul_f32_e32 v16, v3, v15
	v_cndmask_b32_e64 v11, v17, v11, s[22:23]
	v_cndmask_b32_e64 v15, v15, v16, s[22:23]

.LBB0_986:
	v_mov_b32_e32 v121, v145
	v_cvt_pk_bf16_f32 v0, v8, v9
	v_cvt_pk_bf16_f32 v1, v10, v11
	v_cvt_pk_bf16_f32 v2, v12, v13
	v_cvt_pk_bf16_f32 v3, v14, v15
	v_lshl_add_u64 v[4:5], v[24:25], 0, v[120:121]
	global_store_dwordx4 v[4:5], v[0:3], off
	s_andn2_b64 vcc, exec, s[2:3]
	s_mov_b64 s[2:3], -1
	v_lshl_add_u64 v[0:1], s[0:1], 1, v[24:25]
	s_cbranch_vccnz .LBB0_900
	s_andn2_b64 vcc, exec, s[6:7]
	s_cbranch_vccnz .LBB0_899
	s_barrier
	s_branch .LBB0_899

.LBB0_1184:
	v_mov_b32_e32 v114, v212
	s_ashr_i32 s59, s58, 31
	v_readfirstlane_b32 s6, v114
	s_ashr_i32 s7, s6, 6
	s_lshl_b64 s[2:3], s[58:59], 17
	v_readlane_b32 s4, v255, 36
	s_add_u32 s8, s4, s2
	v_readlane_b32 s2, v255, 37
	s_addc_u32 s9, s2, s3
	s_lshl_b32 s4, s7, 2
	s_ashr_i32 s5, s4, 31
	s_lshl_b64 s[2:3], s[4:5], 12
	v_and_b32_e32 v64, 63, v114
	s_add_u32 s2, s8, s2
	s_addc_u32 s3, s9, s3
	v_lshlrev_b32_e32 v112, 2, v64
	v_lshl_add_u64 v[16:17], s[2:3], 0, v[112:113]
	v_lshl_add_u64 v[32:33], v[16:17], 0, s[0:1]
	global_load_dword v0, v112, s[2:3]
	s_waitcnt lgkmcnt(0)
	global_load_dword v1, v112, s[2:3] offset:256
	global_load_dword v2, v112, s[2:3] offset:512
	global_load_dword v3, v112, s[2:3] offset:768
	global_load_dword v4, v112, s[2:3] offset:1024
	global_load_dword v5, v112, s[2:3] offset:1280
	global_load_dword v6, v112, s[2:3] offset:1536
	global_load_dword v7, v112, s[2:3] offset:1792
	global_load_dword v8, v112, s[2:3] offset:2048
	global_load_dword v9, v112, s[2:3] offset:2304
	global_load_dword v10, v112, s[2:3] offset:2560
	global_load_dword v11, v112, s[2:3] offset:2816
	global_load_dword v12, v112, s[2:3] offset:3072
	global_load_dword v13, v112, s[2:3] offset:3328
	global_load_dword v14, v112, s[2:3] offset:3584
	global_load_dword v15, v112, s[2:3] offset:3840
	global_load_dword v16, v[32:33], off
	global_load_dword v17, v[32:33], off offset:256
	global_load_dword v18, v[32:33], off offset:512
	global_load_dword v19, v[32:33], off offset:768
	global_load_dword v20, v[32:33], off offset:1024
	global_load_dword v21, v[32:33], off offset:1280
	global_load_dword v22, v[32:33], off offset:1536
	global_load_dword v23, v[32:33], off offset:1792
	global_load_dword v24, v[32:33], off offset:2048
	global_load_dword v25, v[32:33], off offset:2304
	global_load_dword v26, v[32:33], off offset:2560
	global_load_dword v27, v[32:33], off offset:2816
	global_load_dword v28, v[32:33], off offset:3072
	global_load_dword v29, v[32:33], off offset:3328
	global_load_dword v30, v[32:33], off offset:3584
	global_load_dword v31, v[32:33], off offset:3840
	v_lshl_add_u64 v[48:49], v[32:33], 0, s[0:1]
	global_load_dword v32, v[48:49], off
	global_load_dword v33, v[48:49], off offset:256
	global_load_dword v34, v[48:49], off offset:512
	global_load_dword v35, v[48:49], off offset:768
	global_load_dword v36, v[48:49], off offset:1024
	global_load_dword v37, v[48:49], off offset:1280
	global_load_dword v38, v[48:49], off offset:1536
	global_load_dword v39, v[48:49], off offset:1792
	global_load_dword v40, v[48:49], off offset:2048
	global_load_dword v41, v[48:49], off offset:2304
	global_load_dword v42, v[48:49], off offset:2560
	global_load_dword v43, v[48:49], off offset:2816
	global_load_dword v44, v[48:49], off offset:3072
	global_load_dword v45, v[48:49], off offset:3328
	global_load_dword v46, v[48:49], off offset:3584
	global_load_dword v47, v[48:49], off offset:3840
	v_lshl_add_u64 v[66:67], v[48:49], 0, s[0:1]
	global_load_dword v48, v[66:67], off
	global_load_dword v49, v[66:67], off offset:256
	global_load_dword v50, v[66:67], off offset:512
	global_load_dword v51, v[66:67], off offset:768
	global_load_dword v52, v[66:67], off offset:1024
	global_load_dword v53, v[66:67], off offset:1280
	global_load_dword v54, v[66:67], off offset:1536
	global_load_dword v55, v[66:67], off offset:1792
	global_load_dword v56, v[66:67], off offset:2048
	global_load_dword v57, v[66:67], off offset:2304
	global_load_dword v58, v[66:67], off offset:2560
	global_load_dword v59, v[66:67], off offset:2816
	global_load_dword v60, v[66:67], off offset:3072
	global_load_dword v61, v[66:67], off offset:3328
	global_load_dword v62, v[66:67], off offset:3584
	global_load_dword v63, v[66:67], off offset:3840
	s_movk_i32 s2, 0x7f
	v_lshl_add_u64 v[66:67], v[66:67], 0, s[0:1]
	v_cmp_lt_i32_e32 vcc, s2, v114
	v_ashrrev_i32_e32 v115, 31, v114
	s_and_saveexec_b64 s[2:3], vcc
	s_xor_b64 s[2:3], exec, s[2:3]
	s_andn2_saveexec_b64 s[2:3], s[2:3]
	s_cbranch_execz .LBB0_1186
	s_lshl_b64 s[8:9], s[58:59], 9
	v_readlane_b32 s5, v255, 39
	s_add_u32 s8, s5, s8
	v_readlane_b32 s5, v255, 40
	s_addc_u32 s9, s5, s9
	v_lshl_add_u64 v[66:67], v[114:115], 2, s[8:9]
	global_load_dword v65, v[66:67], off
	v_lshl_add_u32 v66, v114, 2, 0
	v_add_u32_e32 v66, 0x1a700, v66
	s_waitcnt vmcnt(0)
	ds_write_b32 v66, v65

.LBB0_1496:
	s_lshl_b32 s0, s40, 4
	v_cvt_pk_bf16_f32 v128, v128, v129
	v_cvt_pk_bf16_f32 v129, v130, v131
	v_cvt_pk_bf16_f32 v130, v132, v133
	v_cvt_pk_bf16_f32 v131, v134, v135
	s_lshl_b32 s0, s0, 1
	global_store_dwordx4 v[170:171], v[128:131], off offset:256
	v_lshl_add_u64 v[168:169], v[168:169], 0, s[0:1]
	v_mov_b64_e32 v[134:135], v[90:91]
	v_mov_b64_e32 v[130:131], v[94:95]
	s_and_b64 vcc, exec, s[4:5]
	v_mov_b64_e32 v[128:129], v[92:93]
	v_mov_b64_e32 v[132:133], v[88:89]
	s_cbranch_vccnz .LBB0_1498
	v_mul_f32_e32 v129, 0xbfb8aa3b, v88
	v_mul_f32_e32 v130, 0xbfb8aa3b, v93
	v_exp_f32_e32 v129, v129
	v_exp_f32_e32 v130, v130
	v_mul_f32_e32 v131, 0xbfb8aa3b, v94
	v_mul_f32_e32 v133, 0xbfb8aa3b, v90
	v_add_f32_e32 v129, 1.0, v129
	v_rcp_f32_e32 v132, v129
	v_add_f32_e32 v129, 1.0, v130
	v_mul_f32_e32 v130, 0xbfb8aa3b, v89
	v_exp_f32_e32 v130, v130
	v_exp_f32_e32 v131, v131
	v_exp_f32_e32 v133, v133
	v_mul_f32_e32 v128, 0xbfb8aa3b, v92
	v_add_f32_e32 v163, 1.0, v130
	v_add_f32_e32 v130, 1.0, v131
	v_add_f32_e32 v131, 1.0, v133
	v_mul_f32_e32 v133, 0xbfb8aa3b, v95
	v_mul_f32_e32 v134, 0xbfb8aa3b, v91
	v_exp_f32_e32 v128, v128
	v_exp_f32_e32 v133, v133
	v_exp_f32_e32 v135, v134
	v_rcp_f32_e32 v134, v131
	v_add_f32_e32 v128, 1.0, v128
	v_add_f32_e32 v131, 1.0, v133
	v_add_f32_e32 v133, 1.0, v135
	v_rcp_f32_e32 v128, v128
	v_rcp_f32_e32 v129, v129
	v_rcp_f32_e32 v130, v130
	v_rcp_f32_e32 v131, v131
	v_rcp_f32_e32 v135, v133
	v_rcp_f32_e32 v133, v163
	v_pk_mul_f32 v[128:129], v[92:93], v[128:129]
	v_pk_mul_f32 v[130:131], v[94:95], v[130:131]
	v_pk_mul_f32 v[134:135], v[90:91], v[134:135]
	v_pk_mul_f32 v[132:133], v[88:89], v[132:133]

.LBB0_1504:
	s_mul_i32 s33, s40, 0x50
	v_cvt_pk_bf16_f32 v128, v128, v129
	v_cvt_pk_bf16_f32 v129, v130, v131
	v_cvt_pk_bf16_f32 v130, v132, v133
	v_cvt_pk_bf16_f32 v131, v134, v135
	s_lshl_b32 s40, s33, 1
	s_mov_b32 s41, s1
	global_store_dwordx4 v[170:171], v[128:131], off offset:256
	v_lshl_add_u64 v[168:169], v[168:169], 0, s[40:41]
	v_mov_b64_e32 v[134:135], v[58:59]
	v_mov_b64_e32 v[130:131], v[62:63]
	s_and_b64 vcc, exec, s[4:5]
	v_mov_b64_e32 v[128:129], v[60:61]
	v_mov_b64_e32 v[132:133], v[56:57]
	s_cbranch_vccnz .LBB0_1506
	v_mul_f32_e32 v129, 0xbfb8aa3b, v56
	v_mul_f32_e32 v130, 0xbfb8aa3b, v61
	v_exp_f32_e32 v129, v129
	v_exp_f32_e32 v130, v130
	v_mul_f32_e32 v131, 0xbfb8aa3b, v62
	v_mul_f32_e32 v133, 0xbfb8aa3b, v58
	v_add_f32_e32 v129, 1.0, v129
	v_rcp_f32_e32 v132, v129
	v_add_f32_e32 v129, 1.0, v130
	v_mul_f32_e32 v130, 0xbfb8aa3b, v57
	v_exp_f32_e32 v130, v130
	v_exp_f32_e32 v131, v131
	v_exp_f32_e32 v133, v133
	v_mul_f32_e32 v128, 0xbfb8aa3b, v60
	v_add_f32_e32 v163, 1.0, v130
	v_add_f32_e32 v130, 1.0, v131
	v_add_f32_e32 v131, 1.0, v133
	v_mul_f32_e32 v133, 0xbfb8aa3b, v63
	v_mul_f32_e32 v134, 0xbfb8aa3b, v59
	v_exp_f32_e32 v128, v128
	v_exp_f32_e32 v133, v133
	v_exp_f32_e32 v135, v134
	v_rcp_f32_e32 v134, v131
	v_add_f32_e32 v128, 1.0, v128
	v_add_f32_e32 v131, 1.0, v133
	v_add_f32_e32 v133, 1.0, v135
	v_rcp_f32_e32 v128, v128
	v_rcp_f32_e32 v129, v129
	v_rcp_f32_e32 v130, v130
	v_rcp_f32_e32 v131, v131
	v_rcp_f32_e32 v135, v133
	v_rcp_f32_e32 v133, v163
	v_pk_mul_f32 v[128:129], v[60:61], v[128:129]
	v_pk_mul_f32 v[130:131], v[62:63], v[130:131]
	v_pk_mul_f32 v[134:135], v[58:59], v[134:135]
	v_pk_mul_f32 v[132:133], v[56:57], v[132:133]

.LBB0_1520:
	v_cvt_pk_bf16_f32 v128, v128, v129
	v_cvt_pk_bf16_f32 v129, v130, v131
	v_cvt_pk_bf16_f32 v130, v132, v133
	v_cvt_pk_bf16_f32 v131, v134, v135
	s_mov_b32 s41, s1
	global_store_dwordx4 v[170:171], v[128:131], off offset:256
	s_mov_b64 s[4:5], 0
	s_nop 0
	v_lshl_add_u64 v[128:129], v[168:169], 0, s[40:41]
